# page loop: exp2f denormal-range expansion -> v_exp_f32 (results below 2^-126 flush to zero) on top of the mixed mixer-A order
# speedup vs baseline: 1.1158x; 1.0066x over previous
.LBB0_323:
	s_waitcnt vmcnt(33)
	v_pk_mul_f32 v[134:135], v[116:117], v[52:53]
	s_waitcnt vmcnt(8)
	v_add_f32_e32 v155, v171, v146
	v_pk_fma_f32 v[134:135], v[114:115], v[50:51], v[134:135]
	v_mov_b32_e32 v147, v167
	v_add_f32_e32 v134, v134, v135
	v_add_f32_e32 v167, v170, v155
	v_add_f32_e32 v154, v169, v167
	v_add_f32_dpp v134, v134, v134 quad_perm:[1,0,3,2] row_mask:0xf bank_mask:0xf bound_ctrl:1
	s_nop 1
	v_add_f32_dpp v134, v134, v134 quad_perm:[2,3,0,1] row_mask:0xf bank_mask:0xf bound_ctrl:1
	s_nop 1
	v_add_f32_dpp v134, v134, v134 row_half_mirror row_mask:0xf bank_mask:0xf bound_ctrl:1
	s_nop 1
	v_add_f32_dpp v136, v134, v134 row_mirror row_mask:0xf bank_mask:0xf bound_ctrl:1
	v_pk_mul_f32 v[134:135], v[116:117], v[60:61]
	v_fmac_f32_e32 v136, 0x3fb8aa3b, v154
	v_pk_fma_f32 v[134:135], v[114:115], v[58:59], v[134:135]
	s_nop 0
	v_add_f32_e32 v134, v134, v135
	s_nop 1
	v_add_f32_dpp v134, v134, v134 quad_perm:[1,0,3,2] row_mask:0xf bank_mask:0xf bound_ctrl:1
	s_nop 1
	v_add_f32_dpp v134, v134, v134 quad_perm:[2,3,0,1] row_mask:0xf bank_mask:0xf bound_ctrl:1
	s_nop 1
	v_add_f32_dpp v134, v134, v134 row_half_mirror row_mask:0xf bank_mask:0xf bound_ctrl:1
	s_nop 1
	v_add_f32_dpp v137, v134, v134 row_mirror row_mask:0xf bank_mask:0xf bound_ctrl:1
	v_pk_mul_f32 v[134:135], v[116:117], v[56:57]
	v_fmac_f32_e32 v137, 0x3fb8aa3b, v167
	v_pk_fma_f32 v[134:135], v[114:115], v[54:55], v[134:135]
	s_nop 0
	v_add_f32_e32 v134, v134, v135
	s_nop 1
	v_add_f32_dpp v134, v134, v134 quad_perm:[1,0,3,2] row_mask:0xf bank_mask:0xf bound_ctrl:1
	s_nop 1
	v_add_f32_dpp v134, v134, v134 quad_perm:[2,3,0,1] row_mask:0xf bank_mask:0xf bound_ctrl:1
	s_nop 1
	v_add_f32_dpp v134, v134, v134 row_half_mirror row_mask:0xf bank_mask:0xf bound_ctrl:1
	s_nop 1
	v_add_f32_dpp v139, v134, v134 row_mirror row_mask:0xf bank_mask:0xf bound_ctrl:1
	v_pk_mul_f32 v[134:135], v[116:117], v[64:65]
	v_fmac_f32_e32 v139, 0x3fb8aa3b, v155
	v_pk_fma_f32 v[134:135], v[114:115], v[62:63], v[134:135]
	s_nop 0
	v_add_f32_e32 v134, v134, v135
	s_nop 1
	v_add_f32_dpp v134, v134, v134 quad_perm:[1,0,3,2] row_mask:0xf bank_mask:0xf bound_ctrl:1
	s_nop 1
	v_add_f32_dpp v134, v134, v134 quad_perm:[2,3,0,1] row_mask:0xf bank_mask:0xf bound_ctrl:1
	s_nop 1
	v_add_f32_dpp v134, v134, v134 row_half_mirror row_mask:0xf bank_mask:0xf bound_ctrl:1
	s_nop 1
	v_add_f32_dpp v135, v134, v134 row_mirror row_mask:0xf bank_mask:0xf bound_ctrl:1
	v_fmac_f32_e32 v135, 0x3fb8aa3b, v146
	v_max_f32_e32 v134, v136, v137
	v_max_f32_e32 v138, v139, v135
	v_max3_f32 v148, v151, v134, v138
	v_sub_f32_e32 v134, v151, v148
	v_sub_f32_e32 v136, v136, v148
	v_sub_f32_e32 v137, v137, v148
	v_exp_f32_e32 v134, v134
	v_sub_f32_e32 v135, v135, v148
	v_exp_f32_e32 v136, v136
	v_exp_f32_e32 v137, v137
	s_nop 0
	v_mov_b32_e32 v138, v137
	v_sub_f32_e32 v137, v139, v148
	v_exp_f32_e32 v137, v137
	v_exp_f32_e32 v135, v135
	v_pk_mul_f32 v[152:153], v[136:137], v[22:23] op_sel_hi:[0,1]
	v_mov_b32_e32 v139, v135
	v_pk_add_f32 v[140:141], v[136:137], v[138:139]
	v_pk_fma_f32 v[132:133], v[132:133], v[134:135], v[152:153] op_sel_hi:[1,0,1]
	v_add_f32_e32 v175, v140, v141
	v_pk_mul_f32 v[140:141], v[136:137], v[24:25] op_sel_hi:[0,1]
	v_pk_fma_f32 v[130:131], v[130:131], v[134:135], v[140:141] op_sel_hi:[1,0,1]
	v_fmac_f32_e32 v175, v98, v134
	v_pk_fma_f32 v[130:131], v[138:139], v[20:21], v[130:131] op_sel_hi:[0,1,1]
	v_pk_fma_f32 v[132:133], v[138:139], v[18:19], v[132:133] op_sel_hi:[0,1,1]
	v_mov_b32_e32 v98, v137
	v_pk_fma_f32 v[132:133], v[98:99], v[26:27], v[132:133] op_sel_hi:[0,1,1]
	v_pk_fma_f32 v[130:131], v[98:99], v[28:29], v[130:131] op_sel_hi:[0,1,1]
	v_mov_b32_e32 v98, v139
	v_pk_fma_f32 v[134:135], v[98:99], v[32:33], v[130:131] op_sel_hi:[0,1,1]
	v_pk_fma_f32 v[136:137], v[98:99], v[30:31], v[132:133] op_sel_hi:[0,1,1]
	v_pk_mul_f32 v[130:131], v[112:113], v[52:53]
	s_nop 0
	v_pk_fma_f32 v[130:131], v[110:111], v[50:51], v[130:131]
	s_nop 0
	v_add_f32_e32 v98, v130, v131
	v_pk_mul_f32 v[130:131], v[112:113], v[60:61]
	s_nop 0
	v_add_f32_dpp v98, v98, v98 quad_perm:[1,0,3,2] row_mask:0xf bank_mask:0xf bound_ctrl:1
	v_pk_fma_f32 v[130:131], v[110:111], v[58:59], v[130:131]
	s_nop 0
	v_add_f32_dpp v98, v98, v98 quad_perm:[2,3,0,1] row_mask:0xf bank_mask:0xf bound_ctrl:1
	s_nop 1
	v_add_f32_dpp v98, v98, v98 row_half_mirror row_mask:0xf bank_mask:0xf bound_ctrl:1
	s_nop 1
	v_add_f32_dpp v132, v98, v98 row_mirror row_mask:0xf bank_mask:0xf bound_ctrl:1
	v_add_f32_e32 v98, v130, v131
	v_pk_mul_f32 v[130:131], v[112:113], v[56:57]
	v_fmac_f32_e32 v132, 0x3fb8aa3b, v154
	v_add_f32_dpp v98, v98, v98 quad_perm:[1,0,3,2] row_mask:0xf bank_mask:0xf bound_ctrl:1
	v_pk_fma_f32 v[130:131], v[110:111], v[54:55], v[130:131]
	s_nop 0
	v_add_f32_dpp v98, v98, v98 quad_perm:[2,3,0,1] row_mask:0xf bank_mask:0xf bound_ctrl:1
	s_nop 1
	v_add_f32_dpp v98, v98, v98 row_half_mirror row_mask:0xf bank_mask:0xf bound_ctrl:1
	s_nop 1
	v_add_f32_dpp v133, v98, v98 row_mirror row_mask:0xf bank_mask:0xf bound_ctrl:1
	v_add_f32_e32 v98, v130, v131
	v_pk_mul_f32 v[130:131], v[112:113], v[64:65]
	v_fmac_f32_e32 v133, 0x3fb8aa3b, v167
	v_add_f32_dpp v98, v98, v98 quad_perm:[1,0,3,2] row_mask:0xf bank_mask:0xf bound_ctrl:1
	v_pk_fma_f32 v[130:131], v[110:111], v[62:63], v[130:131]
	s_nop 0
	v_add_f32_dpp v98, v98, v98 quad_perm:[2,3,0,1] row_mask:0xf bank_mask:0xf bound_ctrl:1
	s_nop 1
	v_add_f32_dpp v98, v98, v98 row_half_mirror row_mask:0xf bank_mask:0xf bound_ctrl:1
	s_nop 1
	v_add_f32_dpp v139, v98, v98 row_mirror row_mask:0xf bank_mask:0xf bound_ctrl:1
	v_add_f32_e32 v98, v130, v131
	v_fmac_f32_e32 v139, 0x3fb8aa3b, v155
	s_nop 0
	v_add_f32_dpp v98, v98, v98 quad_perm:[1,0,3,2] row_mask:0xf bank_mask:0xf bound_ctrl:1
	s_nop 1
	v_add_f32_dpp v98, v98, v98 quad_perm:[2,3,0,1] row_mask:0xf bank_mask:0xf bound_ctrl:1
	s_nop 1
	v_add_f32_dpp v98, v98, v98 row_half_mirror row_mask:0xf bank_mask:0xf bound_ctrl:1
	s_nop 1
	v_add_f32_dpp v130, v98, v98 row_mirror row_mask:0xf bank_mask:0xf bound_ctrl:1
	v_fmac_f32_e32 v130, 0x3fb8aa3b, v146
	v_max_f32_e32 v98, v132, v133
	v_max_f32_e32 v131, v139, v130
	v_max3_f32 v131, v150, v98, v131
	v_sub_f32_e32 v98, v150, v131
	v_sub_f32_e32 v132, v132, v131
	v_sub_f32_e32 v130, v130, v131
	v_exp_f32_e32 v98, v98
	v_exp_f32_e32 v132, v132
	s_nop 0
	v_mov_b32_e32 v138, v132
	v_sub_f32_e32 v132, v133, v131
	v_pk_mul_f32 v[156:157], v[138:139], v[24:25] op_sel_hi:[0,1]
	v_pk_fma_f32 v[126:127], v[126:127], v[98:99], v[156:157] op_sel_hi:[1,0,1]
	v_exp_f32_e32 v132, v132
	s_nop 0
	v_mov_b32_e32 v140, v132
	v_sub_f32_e32 v132, v139, v131
	v_pk_fma_f32 v[126:127], v[140:141], v[20:21], v[126:127] op_sel_hi:[0,1,1]
	v_exp_f32_e32 v132, v132
	s_nop 0
	v_mov_b32_e32 v150, v132
	v_exp_f32_e32 v130, v130
	v_pk_fma_f32 v[126:127], v[150:151], v[28:29], v[126:127] op_sel_hi:[0,1,1]
	v_mov_b32_e32 v152, v130
	v_add_f32_e32 v132, v138, v140
	v_pk_mul_f32 v[138:139], v[138:139], v[22:23] op_sel_hi:[0,1]
	v_pk_fma_f32 v[128:129], v[128:129], v[98:99], v[138:139] op_sel_hi:[1,0,1]
	v_add_f32_e32 v130, v150, v152
	v_pk_fma_f32 v[128:129], v[140:141], v[18:19], v[128:129] op_sel_hi:[0,1,1]
	v_pk_fma_f32 v[128:129], v[150:151], v[26:27], v[128:129] op_sel_hi:[0,1,1]
	v_pk_fma_f32 v[126:127], v[152:153], v[32:33], v[126:127] op_sel_hi:[0,1,1]
	v_pk_fma_f32 v[128:129], v[152:153], v[30:31], v[128:129] op_sel_hi:[0,1,1]
	v_pk_mul_f32 v[138:139], v[108:109], v[52:53]
	s_nop 0
	v_pk_fma_f32 v[138:139], v[106:107], v[50:51], v[138:139]
	s_nop 0
	v_add_f32_e32 v133, v138, v139
	v_pk_mul_f32 v[138:139], v[108:109], v[60:61]
	s_nop 0
	v_pk_fma_f32 v[138:139], v[106:107], v[58:59], v[138:139]
	v_add_f32_dpp v133, v133, v133 quad_perm:[1,0,3,2] row_mask:0xf bank_mask:0xf bound_ctrl:1
	v_add_f32_e32 v138, v138, v139
	s_nop 0
	v_add_f32_dpp v133, v133, v133 quad_perm:[2,3,0,1] row_mask:0xf bank_mask:0xf bound_ctrl:1
	v_add_f32_dpp v138, v138, v138 quad_perm:[1,0,3,2] row_mask:0xf bank_mask:0xf bound_ctrl:1
	s_nop 0
	v_add_f32_dpp v133, v133, v133 row_half_mirror row_mask:0xf bank_mask:0xf bound_ctrl:1
	v_add_f32_dpp v138, v138, v138 quad_perm:[2,3,0,1] row_mask:0xf bank_mask:0xf bound_ctrl:1
	s_nop 0
	v_add_f32_dpp v133, v133, v133 row_mirror row_mask:0xf bank_mask:0xf bound_ctrl:1
	v_add_f32_dpp v138, v138, v138 row_half_mirror row_mask:0xf bank_mask:0xf bound_ctrl:1
	v_fmac_f32_e32 v133, 0x3fb8aa3b, v154
	s_nop 0
	v_add_f32_dpp v141, v138, v138 row_mirror row_mask:0xf bank_mask:0xf bound_ctrl:1
	v_pk_mul_f32 v[138:139], v[108:109], v[56:57]
	v_fmac_f32_e32 v141, 0x3fb8aa3b, v167
	v_pk_fma_f32 v[138:139], v[106:107], v[54:55], v[138:139]
	s_nop 0
	v_add_f32_e32 v138, v138, v139
	s_nop 1
	v_add_f32_dpp v138, v138, v138 quad_perm:[1,0,3,2] row_mask:0xf bank_mask:0xf bound_ctrl:1
	s_nop 1
	v_add_f32_dpp v138, v138, v138 quad_perm:[2,3,0,1] row_mask:0xf bank_mask:0xf bound_ctrl:1
	s_nop 1
	v_add_f32_dpp v138, v138, v138 row_half_mirror row_mask:0xf bank_mask:0xf bound_ctrl:1
	s_nop 1
	v_add_f32_dpp v151, v138, v138 row_mirror row_mask:0xf bank_mask:0xf bound_ctrl:1
	v_pk_mul_f32 v[138:139], v[108:109], v[64:65]
	v_fmac_f32_e32 v151, 0x3fb8aa3b, v155
	v_pk_fma_f32 v[138:139], v[106:107], v[62:63], v[138:139]
	s_nop 0
	v_add_f32_e32 v138, v138, v139
	s_nop 1
	v_add_f32_dpp v138, v138, v138 quad_perm:[1,0,3,2] row_mask:0xf bank_mask:0xf bound_ctrl:1
	s_nop 1
	v_add_f32_dpp v138, v138, v138 quad_perm:[2,3,0,1] row_mask:0xf bank_mask:0xf bound_ctrl:1
	s_nop 1
	v_add_f32_dpp v138, v138, v138 row_half_mirror row_mask:0xf bank_mask:0xf bound_ctrl:1
	s_nop 1
	v_add_f32_dpp v139, v138, v138 row_mirror row_mask:0xf bank_mask:0xf bound_ctrl:1
	v_fmac_f32_e32 v139, 0x3fb8aa3b, v146
	v_max_f32_e32 v138, v133, v141
	v_max_f32_e32 v140, v151, v139
	v_max3_f32 v149, v144, v138, v140
	v_sub_f32_e32 v138, v144, v149
	v_sub_f32_e32 v133, v133, v149
	v_exp_f32_e32 v138, v138
	v_exp_f32_e32 v133, v133
	s_nop 0
	v_mov_b32_e32 v140, v133
	v_sub_f32_e32 v133, v141, v149
	v_exp_f32_e32 v133, v133
	s_nop 0
	v_mov_b32_e32 v150, v133
	v_sub_f32_e32 v133, v151, v149
	v_exp_f32_e32 v133, v133
	s_nop 0
	v_mov_b32_e32 v141, v133
	v_sub_f32_e32 v133, v139, v149
	v_pk_mul_f32 v[156:157], v[140:141], v[22:23] op_sel_hi:[0,1]
	v_exp_f32_e32 v133, v133
	v_pk_fma_f32 v[124:125], v[124:125], v[138:139], v[156:157] op_sel_hi:[1,0,1]
	v_mov_b32_e32 v151, v133
	v_pk_add_f32 v[152:153], v[140:141], v[150:151]
	v_pk_fma_f32 v[124:125], v[150:151], v[18:19], v[124:125] op_sel_hi:[0,1,1]
	v_add_f32_e32 v173, v152, v153
	v_pk_mul_f32 v[152:153], v[140:141], v[24:25] op_sel_hi:[0,1]
	v_pk_fma_f32 v[122:123], v[122:123], v[138:139], v[152:153] op_sel_hi:[1,0,1]
	v_fmac_f32_e32 v173, v100, v138
	v_pk_fma_f32 v[122:123], v[150:151], v[20:21], v[122:123] op_sel_hi:[0,1,1]
	v_mov_b32_e32 v100, v141
	v_pk_fma_f32 v[124:125], v[100:101], v[26:27], v[124:125] op_sel_hi:[0,1,1]
	v_pk_fma_f32 v[122:123], v[100:101], v[28:29], v[122:123] op_sel_hi:[0,1,1]
	v_mov_b32_e32 v100, v151
	v_pk_fma_f32 v[138:139], v[100:101], v[32:33], v[122:123] op_sel_hi:[0,1,1]
	v_pk_fma_f32 v[140:141], v[100:101], v[30:31], v[124:125] op_sel_hi:[0,1,1]
	v_pk_mul_f32 v[52:53], v[104:105], v[52:53]
	s_nop 0
	v_pk_fma_f32 v[50:51], v[102:103], v[50:51], v[52:53]
	s_nop 0
	v_add_f32_e32 v50, v50, v51
	s_nop 1
	v_add_f32_dpp v50, v50, v50 quad_perm:[1,0,3,2] row_mask:0xf bank_mask:0xf bound_ctrl:1
	s_nop 1
	v_add_f32_dpp v50, v50, v50 quad_perm:[2,3,0,1] row_mask:0xf bank_mask:0xf bound_ctrl:1
	s_nop 1
	v_add_f32_dpp v50, v50, v50 row_half_mirror row_mask:0xf bank_mask:0xf bound_ctrl:1
	s_nop 1
	v_add_f32_dpp v52, v50, v50 row_mirror row_mask:0xf bank_mask:0xf bound_ctrl:1
	v_pk_mul_f32 v[50:51], v[104:105], v[60:61]
	v_fmac_f32_e32 v52, 0x3fb8aa3b, v154
	v_pk_fma_f32 v[50:51], v[102:103], v[58:59], v[50:51]
	s_nop 0
	v_add_f32_e32 v50, v50, v51
	s_nop 1
	v_add_f32_dpp v50, v50, v50 quad_perm:[1,0,3,2] row_mask:0xf bank_mask:0xf bound_ctrl:1
	s_nop 1
	v_add_f32_dpp v50, v50, v50 quad_perm:[2,3,0,1] row_mask:0xf bank_mask:0xf bound_ctrl:1
	s_nop 1
	v_add_f32_dpp v50, v50, v50 row_half_mirror row_mask:0xf bank_mask:0xf bound_ctrl:1
	s_nop 1
	v_add_f32_dpp v53, v50, v50 row_mirror row_mask:0xf bank_mask:0xf bound_ctrl:1
	v_pk_mul_f32 v[50:51], v[104:105], v[56:57]
	v_fmac_f32_e32 v53, 0x3fb8aa3b, v167
	v_pk_fma_f32 v[50:51], v[102:103], v[54:55], v[50:51]
	s_nop 0
	v_add_f32_e32 v50, v50, v51
	s_nop 1
	v_add_f32_dpp v50, v50, v50 quad_perm:[1,0,3,2] row_mask:0xf bank_mask:0xf bound_ctrl:1
	s_nop 1
	v_add_f32_dpp v50, v50, v50 quad_perm:[2,3,0,1] row_mask:0xf bank_mask:0xf bound_ctrl:1
	s_nop 1
	v_add_f32_dpp v50, v50, v50 row_half_mirror row_mask:0xf bank_mask:0xf bound_ctrl:1
	s_nop 1
	v_add_f32_dpp v55, v50, v50 row_mirror row_mask:0xf bank_mask:0xf bound_ctrl:1
	v_pk_mul_f32 v[50:51], v[104:105], v[64:65]
	v_fmac_f32_e32 v55, 0x3fb8aa3b, v155
	v_pk_fma_f32 v[50:51], v[102:103], v[62:63], v[50:51]
	s_nop 0
	v_add_f32_e32 v50, v50, v51
	s_nop 1
	v_add_f32_dpp v50, v50, v50 quad_perm:[1,0,3,2] row_mask:0xf bank_mask:0xf bound_ctrl:1
	s_nop 1
	v_add_f32_dpp v50, v50, v50 quad_perm:[2,3,0,1] row_mask:0xf bank_mask:0xf bound_ctrl:1
	s_nop 1
	v_add_f32_dpp v50, v50, v50 row_half_mirror row_mask:0xf bank_mask:0xf bound_ctrl:1
	s_nop 1
	v_add_f32_dpp v51, v50, v50 row_mirror row_mask:0xf bank_mask:0xf bound_ctrl:1
	v_fmac_f32_e32 v51, 0x3fb8aa3b, v146
	v_max_f32_e32 v50, v52, v53
	v_max_f32_e32 v54, v55, v51
	v_max3_f32 v100, v142, v50, v54
	v_sub_f32_e32 v50, v142, v100
	v_sub_f32_e32 v52, v52, v100
	v_sub_f32_e32 v53, v53, v100
	v_exp_f32_e32 v50, v50
	v_sub_f32_e32 v51, v51, v100
	v_exp_f32_e32 v52, v52
	v_exp_f32_e32 v53, v53
	s_nop 0
	v_mov_b32_e32 v54, v53
	v_sub_f32_e32 v53, v55, v100
	v_exp_f32_e32 v53, v53
	v_exp_f32_e32 v51, v51
	v_pk_mul_f32 v[24:25], v[52:53], v[24:25] op_sel_hi:[0,1]
	v_pk_mul_f32 v[22:23], v[52:53], v[22:23] op_sel_hi:[0,1]
	v_mov_b32_e32 v55, v51
	v_pk_fma_f32 v[22:23], v[118:119], v[50:51], v[22:23] op_sel_hi:[1,0,1]
	v_pk_fma_f32 v[24:25], v[120:121], v[50:51], v[24:25] op_sel_hi:[1,0,1]
	v_pk_fma_f32 v[18:19], v[54:55], v[18:19], v[22:23] op_sel_hi:[0,1,1]
	v_pk_fma_f32 v[20:21], v[54:55], v[20:21], v[24:25] op_sel_hi:[0,1,1]
	v_mov_b32_e32 v22, v53
	v_pk_add_f32 v[56:57], v[52:53], v[54:55]
	v_pk_fma_f32 v[18:19], v[22:23], v[26:27], v[18:19] op_sel_hi:[0,1,1]
	v_pk_fma_f32 v[20:21], v[22:23], v[28:29], v[20:21] op_sel_hi:[0,1,1]
	v_mov_b32_e32 v22, v55
	v_add_f32_e32 v174, v56, v57
	v_pk_fma_f32 v[150:151], v[22:23], v[32:33], v[20:21] op_sel_hi:[0,1,1]
	v_fmac_f32_e32 v174, v101, v50
	v_pk_fma_f32 v[152:153], v[22:23], v[30:31], v[18:19] op_sel_hi:[0,1,1]
	s_add_i32 s0, s8, 0x2000
	s_mov_b32 s6, s14
	s_mov_b32 s7, s15
	buffer_load_dwordx4 v[50:53], v161, s[12:15], s0 offen nt
	buffer_load_dwordx4 v[22:25], v161, s[4:7], s0 offen nt
	s_add_i32 s0, s3, 0x80
	buffer_load_dword v167, v162, s[16:19], s0 offen
	s_add_i32 s0, s8, 0x2400
	buffer_load_dwordx4 v[58:61], v161, s[12:15], s0 offen nt
	buffer_load_dwordx4 v[18:21], v161, s[4:7], s0 offen nt
	s_add_i32 s0, s3, 0x90
	buffer_load_dword v169, v162, s[16:19], s0 offen
	s_add_i32 s0, s8, 0x2800
	buffer_load_dwordx4 v[54:57], v161, s[12:15], s0 offen nt
	buffer_load_dwordx4 v[26:29], v161, s[4:7], s0 offen nt
	s_add_i32 s0, s3, 0xa0
	buffer_load_dword v170, v162, s[16:19], s0 offen
	s_add_i32 s0, s8, 0x2c00
	buffer_load_dwordx4 v[62:65], v161, s[12:15], s0 offen nt
	buffer_load_dwordx4 v[30:33], v161, s[4:7], s0 offen nt
	s_add_i32 s0, s3, 0xb0
	buffer_load_dword v171, v162, s[16:19], s0 offen
	v_add_f32_e32 v176, v147, v154
	v_pk_mul_f32 v[118:119], v[116:117], v[36:37]
	s_waitcnt vmcnt(16)
	v_add_f32_e32 v166, v166, v176
	v_pk_fma_f32 v[118:119], v[114:115], v[34:35], v[118:119]
	v_add_f32_e32 v165, v165, v166
	v_add_f32_e32 v118, v118, v119
	v_add_f32_e32 v164, v164, v165
	v_add_f32_e32 v101, v164, v168
	v_add_f32_dpp v118, v118, v118 quad_perm:[1,0,3,2] row_mask:0xf bank_mask:0xf bound_ctrl:1
	s_nop 1
	v_add_f32_dpp v118, v118, v118 quad_perm:[2,3,0,1] row_mask:0xf bank_mask:0xf bound_ctrl:1
	s_nop 1
	v_add_f32_dpp v118, v118, v118 row_half_mirror row_mask:0xf bank_mask:0xf bound_ctrl:1
	s_nop 1
	v_add_f32_dpp v121, v118, v118 row_mirror row_mask:0xf bank_mask:0xf bound_ctrl:1
	v_pk_mul_f32 v[118:119], v[116:117], v[44:45]
	v_fmac_f32_e32 v121, 0x3fb8aa3b, v164
	v_pk_fma_f32 v[118:119], v[114:115], v[42:43], v[118:119]
	s_nop 0
	v_add_f32_e32 v118, v118, v119
	s_nop 1
	v_add_f32_dpp v118, v118, v118 quad_perm:[1,0,3,2] row_mask:0xf bank_mask:0xf bound_ctrl:1
	s_nop 1
	v_add_f32_dpp v118, v118, v118 quad_perm:[2,3,0,1] row_mask:0xf bank_mask:0xf bound_ctrl:1
	s_nop 1
	v_add_f32_dpp v118, v118, v118 row_half_mirror row_mask:0xf bank_mask:0xf bound_ctrl:1
	s_nop 1
	v_add_f32_dpp v122, v118, v118 row_mirror row_mask:0xf bank_mask:0xf bound_ctrl:1
	v_pk_mul_f32 v[118:119], v[116:117], v[40:41]
	v_fmac_f32_e32 v122, 0x3fb8aa3b, v165
	v_pk_fma_f32 v[118:119], v[114:115], v[38:39], v[118:119]
	s_nop 0
	v_add_f32_e32 v118, v118, v119
	s_nop 1
	v_add_f32_dpp v118, v118, v118 quad_perm:[1,0,3,2] row_mask:0xf bank_mask:0xf bound_ctrl:1
	s_nop 1
	v_add_f32_dpp v118, v118, v118 quad_perm:[2,3,0,1] row_mask:0xf bank_mask:0xf bound_ctrl:1
	s_nop 1
	v_add_f32_dpp v118, v118, v118 row_half_mirror row_mask:0xf bank_mask:0xf bound_ctrl:1
	s_nop 1
	v_add_f32_dpp v123, v118, v118 row_mirror row_mask:0xf bank_mask:0xf bound_ctrl:1
	v_pk_mul_f32 v[118:119], v[116:117], v[48:49]
	v_fmac_f32_e32 v123, 0x3fb8aa3b, v166
	v_pk_fma_f32 v[118:119], v[114:115], v[46:47], v[118:119]
	s_nop 0
	v_add_f32_e32 v118, v118, v119
	s_nop 1
	v_add_f32_dpp v118, v118, v118 quad_perm:[1,0,3,2] row_mask:0xf bank_mask:0xf bound_ctrl:1
	s_nop 1
	v_add_f32_dpp v118, v118, v118 quad_perm:[2,3,0,1] row_mask:0xf bank_mask:0xf bound_ctrl:1
	s_nop 1
	v_add_f32_dpp v118, v118, v118 row_half_mirror row_mask:0xf bank_mask:0xf bound_ctrl:1
	s_nop 1
	v_add_f32_dpp v119, v118, v118 row_mirror row_mask:0xf bank_mask:0xf bound_ctrl:1
	v_fmac_f32_e32 v119, 0x3fb8aa3b, v176
	v_max_f32_e32 v118, v121, v122
	v_max_f32_e32 v120, v123, v119
	v_max3_f32 v125, v148, v118, v120
	v_sub_f32_e32 v118, v148, v125
	v_sub_f32_e32 v119, v119, v125
	v_exp_f32_e32 v118, v118
	s_nop 0
	v_mov_b32_e32 v120, v118
	v_sub_f32_e32 v118, v121, v125
	v_exp_f32_e32 v118, v118
	v_sub_f32_e32 v121, v122, v125
	v_exp_f32_e32 v121, v121
	s_nop 0
	v_mov_b32_e32 v122, v121
	v_sub_f32_e32 v121, v123, v125
	v_add_f32_e32 v144, v118, v122
	v_exp_f32_e32 v121, v121
	s_nop 0
	v_mov_b32_e32 v124, v121
	v_exp_f32_e32 v119, v119
	s_nop 0
	v_mov_b32_e32 v146, v119
	v_pk_mul_f32 v[154:155], v[118:119], v[4:5] op_sel_hi:[0,1]
	v_pk_mul_f32 v[118:119], v[118:119], v[2:3] op_sel_hi:[0,1]
	v_pk_fma_f32 v[118:119], v[136:137], v[120:121], v[118:119] op_sel_hi:[1,0,1]
	v_pk_fma_f32 v[134:135], v[134:135], v[120:121], v[154:155] op_sel_hi:[1,0,1]
	v_pk_fma_f32 v[118:119], v[122:123], v[6:7], v[118:119] op_sel_hi:[0,1,1]
	v_pk_fma_f32 v[134:135], v[122:123], v[8:9], v[134:135] op_sel_hi:[0,1,1]
	v_add_f32_e32 v142, v124, v146
	v_pk_fma_f32 v[118:119], v[124:125], v[10:11], v[118:119] op_sel_hi:[0,1,1]
	v_pk_fma_f32 v[122:123], v[124:125], v[12:13], v[134:135] op_sel_hi:[0,1,1]
	v_pk_fma_f32 v[154:155], v[146:147], v[16:17], v[122:123] op_sel_hi:[0,1,1]
	v_pk_fma_f32 v[156:157], v[146:147], v[14:15], v[118:119] op_sel_hi:[0,1,1]
	v_pk_mul_f32 v[118:119], v[112:113], v[36:37]
	v_mul_f32_e32 v98, v99, v98
	v_pk_fma_f32 v[118:119], v[110:111], v[34:35], v[118:119]
	s_nop 0
	v_add_f32_e32 v118, v118, v119
	s_nop 1
	v_add_f32_dpp v118, v118, v118 quad_perm:[1,0,3,2] row_mask:0xf bank_mask:0xf bound_ctrl:1
	s_nop 1
	v_add_f32_dpp v118, v118, v118 quad_perm:[2,3,0,1] row_mask:0xf bank_mask:0xf bound_ctrl:1
	s_nop 1
	v_add_f32_dpp v118, v118, v118 row_half_mirror row_mask:0xf bank_mask:0xf bound_ctrl:1
	s_nop 1
	v_add_f32_dpp v121, v118, v118 row_mirror row_mask:0xf bank_mask:0xf bound_ctrl:1
	v_pk_mul_f32 v[118:119], v[112:113], v[44:45]
	v_fmac_f32_e32 v121, 0x3fb8aa3b, v164
	v_pk_fma_f32 v[118:119], v[110:111], v[42:43], v[118:119]
	s_nop 0
	v_add_f32_e32 v118, v118, v119
	s_nop 1
	v_add_f32_dpp v118, v118, v118 quad_perm:[1,0,3,2] row_mask:0xf bank_mask:0xf bound_ctrl:1
	s_nop 1
	v_add_f32_dpp v118, v118, v118 quad_perm:[2,3,0,1] row_mask:0xf bank_mask:0xf bound_ctrl:1
	s_nop 1
	v_add_f32_dpp v118, v118, v118 row_half_mirror row_mask:0xf bank_mask:0xf bound_ctrl:1
	s_nop 1
	v_add_f32_dpp v124, v118, v118 row_mirror row_mask:0xf bank_mask:0xf bound_ctrl:1
	v_pk_mul_f32 v[118:119], v[112:113], v[40:41]
	v_fmac_f32_e32 v124, 0x3fb8aa3b, v165
	v_pk_fma_f32 v[118:119], v[110:111], v[38:39], v[118:119]
	s_nop 0
	v_add_f32_e32 v118, v118, v119
	s_nop 1
	v_add_f32_dpp v118, v118, v118 quad_perm:[1,0,3,2] row_mask:0xf bank_mask:0xf bound_ctrl:1
	s_nop 1
	v_add_f32_dpp v118, v118, v118 quad_perm:[2,3,0,1] row_mask:0xf bank_mask:0xf bound_ctrl:1
	s_nop 1
	v_add_f32_dpp v118, v118, v118 row_half_mirror row_mask:0xf bank_mask:0xf bound_ctrl:1
	s_nop 1
	v_add_f32_dpp v133, v118, v118 row_mirror row_mask:0xf bank_mask:0xf bound_ctrl:1
	v_pk_mul_f32 v[118:119], v[112:113], v[48:49]
	v_fmac_f32_e32 v133, 0x3fb8aa3b, v166
	v_pk_fma_f32 v[118:119], v[110:111], v[46:47], v[118:119]
	s_nop 0
	v_add_f32_e32 v118, v118, v119
	s_nop 1
	v_add_f32_dpp v118, v118, v118 quad_perm:[1,0,3,2] row_mask:0xf bank_mask:0xf bound_ctrl:1
	s_nop 1
	v_add_f32_dpp v118, v118, v118 quad_perm:[2,3,0,1] row_mask:0xf bank_mask:0xf bound_ctrl:1
	s_nop 1
	v_add_f32_dpp v118, v118, v118 row_half_mirror row_mask:0xf bank_mask:0xf bound_ctrl:1
	s_nop 1
	v_add_f32_dpp v119, v118, v118 row_mirror row_mask:0xf bank_mask:0xf bound_ctrl:1
	v_fmac_f32_e32 v119, 0x3fb8aa3b, v176
	v_max_f32_e32 v118, v121, v124
	v_max_f32_e32 v122, v133, v119
	v_max3_f32 v123, v131, v118, v122
	v_sub_f32_e32 v118, v131, v123
	v_sub_f32_e32 v121, v121, v123
	v_sub_f32_e32 v119, v119, v123
	v_exp_f32_e32 v118, v118
	v_exp_f32_e32 v121, v121
	s_nop 0
	v_mov_b32_e32 v122, v121
	v_sub_f32_e32 v121, v124, v123
	v_pk_mul_f32 v[136:137], v[122:123], v[2:3] op_sel_hi:[0,1]
	v_exp_f32_e32 v121, v121
	s_nop 0
	v_mov_b32_e32 v124, v121
	v_sub_f32_e32 v121, v133, v123
	v_add_f32_e32 v99, v122, v124
	v_exp_f32_e32 v121, v121
	s_nop 0
	v_mov_b32_e32 v133, v121
	v_exp_f32_e32 v119, v119
	s_nop 0
	v_mov_b32_e32 v131, v119
	v_pk_add_f32 v[134:135], v[132:133], v[130:131]
	v_pk_fma_f32 v[128:129], v[128:129], v[118:119], v[136:137] op_sel_hi:[1,0,1]
	v_pk_add_f32 v[98:99], v[98:99], v[134:135]
	v_pk_mul_f32 v[134:135], v[122:123], v[4:5] op_sel_hi:[0,1]
	v_fmac_f32_e32 v99, v98, v118
	v_pk_fma_f32 v[118:119], v[126:127], v[118:119], v[134:135] op_sel_hi:[1,0,1]
	v_pk_fma_f32 v[126:127], v[124:125], v[6:7], v[128:129] op_sel_hi:[0,1,1]
	v_pk_fma_f32 v[118:119], v[124:125], v[8:9], v[118:119] op_sel_hi:[0,1,1]
	v_mov_b32_e32 v98, v133
	v_pk_fma_f32 v[128:129], v[98:99], v[10:11], v[126:127] op_sel_hi:[0,1,1]
	v_pk_fma_f32 v[118:119], v[98:99], v[12:13], v[118:119] op_sel_hi:[0,1,1]
	v_mov_b32_e32 v98, v131
	v_pk_fma_f32 v[126:127], v[98:99], v[16:17], v[118:119] op_sel_hi:[0,1,1]
	v_pk_fma_f32 v[128:129], v[98:99], v[14:15], v[128:129] op_sel_hi:[0,1,1]
	v_pk_mul_f32 v[118:119], v[108:109], v[36:37]
	s_nop 0
	v_pk_fma_f32 v[118:119], v[106:107], v[34:35], v[118:119]
	s_nop 0
	v_add_f32_e32 v98, v118, v119
	v_pk_mul_f32 v[118:119], v[108:109], v[44:45]
	s_nop 0
	v_pk_fma_f32 v[118:119], v[106:107], v[42:43], v[118:119]
	v_add_f32_dpp v98, v98, v98 quad_perm:[1,0,3,2] row_mask:0xf bank_mask:0xf bound_ctrl:1
	v_add_f32_e32 v118, v118, v119
	s_nop 0
	v_add_f32_dpp v98, v98, v98 quad_perm:[2,3,0,1] row_mask:0xf bank_mask:0xf bound_ctrl:1
	v_add_f32_dpp v118, v118, v118 quad_perm:[1,0,3,2] row_mask:0xf bank_mask:0xf bound_ctrl:1
	s_nop 0
	v_add_f32_dpp v98, v98, v98 row_half_mirror row_mask:0xf bank_mask:0xf bound_ctrl:1
	v_add_f32_dpp v118, v118, v118 quad_perm:[2,3,0,1] row_mask:0xf bank_mask:0xf bound_ctrl:1
	s_nop 0
	v_add_f32_dpp v98, v98, v98 row_mirror row_mask:0xf bank_mask:0xf bound_ctrl:1
	v_add_f32_dpp v118, v118, v118 row_half_mirror row_mask:0xf bank_mask:0xf bound_ctrl:1
	v_fmac_f32_e32 v98, 0x3fb8aa3b, v164
	s_nop 0
	v_add_f32_dpp v122, v118, v118 row_mirror row_mask:0xf bank_mask:0xf bound_ctrl:1
	v_pk_mul_f32 v[118:119], v[108:109], v[40:41]
	v_fmac_f32_e32 v122, 0x3fb8aa3b, v165
	v_pk_fma_f32 v[118:119], v[106:107], v[38:39], v[118:119]
	s_nop 0
	v_add_f32_e32 v118, v118, v119
	s_nop 1
	v_add_f32_dpp v118, v118, v118 quad_perm:[1,0,3,2] row_mask:0xf bank_mask:0xf bound_ctrl:1
	s_nop 1
	v_add_f32_dpp v118, v118, v118 quad_perm:[2,3,0,1] row_mask:0xf bank_mask:0xf bound_ctrl:1
	s_nop 1
	v_add_f32_dpp v118, v118, v118 row_half_mirror row_mask:0xf bank_mask:0xf bound_ctrl:1
	s_nop 1
	v_add_f32_dpp v124, v118, v118 row_mirror row_mask:0xf bank_mask:0xf bound_ctrl:1
	v_pk_mul_f32 v[118:119], v[108:109], v[48:49]
	v_fmac_f32_e32 v124, 0x3fb8aa3b, v166
	v_pk_fma_f32 v[118:119], v[106:107], v[46:47], v[118:119]
	s_nop 0
	v_add_f32_e32 v118, v118, v119
	s_nop 1
	v_add_f32_dpp v118, v118, v118 quad_perm:[1,0,3,2] row_mask:0xf bank_mask:0xf bound_ctrl:1
	s_nop 1
	v_add_f32_dpp v118, v118, v118 quad_perm:[2,3,0,1] row_mask:0xf bank_mask:0xf bound_ctrl:1
	s_nop 1
	v_add_f32_dpp v118, v118, v118 row_half_mirror row_mask:0xf bank_mask:0xf bound_ctrl:1
	s_nop 1
	v_add_f32_dpp v119, v118, v118 row_mirror row_mask:0xf bank_mask:0xf bound_ctrl:1
	v_fmac_f32_e32 v119, 0x3fb8aa3b, v176
	v_max_f32_e32 v118, v98, v122
	v_max_f32_e32 v121, v124, v119
	v_max3_f32 v121, v149, v118, v121
	v_sub_f32_e32 v118, v149, v121
	v_sub_f32_e32 v98, v98, v121
	v_sub_f32_e32 v122, v122, v121
	v_exp_f32_e32 v118, v118
	v_sub_f32_e32 v119, v119, v121
	v_exp_f32_e32 v98, v98
	v_exp_f32_e32 v122, v122
	v_pk_mul_f32 v[136:137], v[98:99], v[4:5] op_sel_hi:[0,1]
	v_pk_mul_f32 v[146:147], v[98:99], v[2:3] op_sel_hi:[0,1]
	v_mov_b32_e32 v130, v122
	v_sub_f32_e32 v122, v124, v121
	v_exp_f32_e32 v122, v122
	s_nop 0
	v_mov_b32_e32 v132, v122
	v_exp_f32_e32 v119, v119
	v_add_f32_e32 v124, v98, v130
	v_pk_fma_f32 v[140:141], v[140:141], v[118:119], v[146:147] op_sel_hi:[1,0,1]
	v_pk_fma_f32 v[136:137], v[138:139], v[118:119], v[136:137] op_sel_hi:[1,0,1]
	v_mov_b32_e32 v134, v119
	v_pk_fma_f32 v[136:137], v[130:131], v[8:9], v[136:137] op_sel_hi:[0,1,1]
	v_pk_fma_f32 v[130:131], v[130:131], v[6:7], v[140:141] op_sel_hi:[0,1,1]
	v_add_f32_e32 v122, v132, v134
	v_pk_fma_f32 v[130:131], v[132:133], v[10:11], v[130:131] op_sel_hi:[0,1,1]
	v_pk_fma_f32 v[132:133], v[132:133], v[12:13], v[136:137] op_sel_hi:[0,1,1]
	v_pk_fma_f32 v[146:147], v[134:135], v[16:17], v[132:133] op_sel_hi:[0,1,1]
	v_pk_fma_f32 v[148:149], v[134:135], v[14:15], v[130:131] op_sel_hi:[0,1,1]
	v_pk_mul_f32 v[36:37], v[104:105], v[36:37]
	s_nop 0
	v_pk_fma_f32 v[34:35], v[102:103], v[34:35], v[36:37]
	s_nop 0
	v_add_f32_e32 v34, v34, v35
	s_nop 1
	v_add_f32_dpp v34, v34, v34 quad_perm:[1,0,3,2] row_mask:0xf bank_mask:0xf bound_ctrl:1
	s_nop 1
	v_add_f32_dpp v34, v34, v34 quad_perm:[2,3,0,1] row_mask:0xf bank_mask:0xf bound_ctrl:1
	s_nop 1
	v_add_f32_dpp v34, v34, v34 row_half_mirror row_mask:0xf bank_mask:0xf bound_ctrl:1
	s_nop 1
	v_add_f32_dpp v36, v34, v34 row_mirror row_mask:0xf bank_mask:0xf bound_ctrl:1
	v_pk_mul_f32 v[34:35], v[104:105], v[44:45]
	v_fmac_f32_e32 v36, 0x3fb8aa3b, v164
	v_pk_fma_f32 v[34:35], v[102:103], v[42:43], v[34:35]
	s_nop 0
	v_add_f32_e32 v34, v34, v35
	s_nop 1
	v_add_f32_dpp v34, v34, v34 quad_perm:[1,0,3,2] row_mask:0xf bank_mask:0xf bound_ctrl:1
	s_nop 1
	v_add_f32_dpp v34, v34, v34 quad_perm:[2,3,0,1] row_mask:0xf bank_mask:0xf bound_ctrl:1
	s_nop 1
	v_add_f32_dpp v34, v34, v34 row_half_mirror row_mask:0xf bank_mask:0xf bound_ctrl:1
	s_nop 1
	v_add_f32_dpp v37, v34, v34 row_mirror row_mask:0xf bank_mask:0xf bound_ctrl:1
	v_pk_mul_f32 v[34:35], v[104:105], v[40:41]
	v_fmac_f32_e32 v37, 0x3fb8aa3b, v165
	v_pk_fma_f32 v[34:35], v[102:103], v[38:39], v[34:35]
	s_nop 0
	v_add_f32_e32 v34, v34, v35
	s_nop 1
	v_add_f32_dpp v34, v34, v34 quad_perm:[1,0,3,2] row_mask:0xf bank_mask:0xf bound_ctrl:1
	s_nop 1
	v_add_f32_dpp v34, v34, v34 quad_perm:[2,3,0,1] row_mask:0xf bank_mask:0xf bound_ctrl:1
	s_nop 1
	v_add_f32_dpp v34, v34, v34 row_half_mirror row_mask:0xf bank_mask:0xf bound_ctrl:1
	s_nop 1
	v_add_f32_dpp v38, v34, v34 row_mirror row_mask:0xf bank_mask:0xf bound_ctrl:1
	v_pk_mul_f32 v[34:35], v[104:105], v[48:49]
	v_fmac_f32_e32 v38, 0x3fb8aa3b, v166
	v_pk_fma_f32 v[34:35], v[102:103], v[46:47], v[34:35]
	s_nop 0
	v_add_f32_e32 v34, v34, v35
	s_nop 1
	v_add_f32_dpp v34, v34, v34 quad_perm:[1,0,3,2] row_mask:0xf bank_mask:0xf bound_ctrl:1
	s_nop 1
	v_add_f32_dpp v34, v34, v34 quad_perm:[2,3,0,1] row_mask:0xf bank_mask:0xf bound_ctrl:1
	s_nop 1
	v_add_f32_dpp v34, v34, v34 row_half_mirror row_mask:0xf bank_mask:0xf bound_ctrl:1
	s_nop 1
	v_add_f32_dpp v35, v34, v34 row_mirror row_mask:0xf bank_mask:0xf bound_ctrl:1
	v_fmac_f32_e32 v35, 0x3fb8aa3b, v176
	v_max_f32_e32 v34, v36, v37
	v_max_f32_e32 v39, v38, v35
	v_max3_f32 v119, v100, v34, v39
	v_sub_f32_e32 v34, v100, v119
	v_sub_f32_e32 v35, v35, v119
	v_exp_f32_e32 v34, v34
	s_nop 0
	v_mov_b32_e32 v100, v34
	v_sub_f32_e32 v34, v36, v119
	v_exp_f32_e32 v34, v34
	v_sub_f32_e32 v36, v37, v119
	v_exp_f32_e32 v36, v36
	v_sub_f32_e32 v37, v38, v119
	v_add_f32_e32 v136, v34, v36
	v_exp_f32_e32 v37, v37
	s_nop 0
	v_mov_b32_e32 v38, v37
	v_exp_f32_e32 v35, v35
	s_nop 0
	v_pk_mul_f32 v[4:5], v[34:35], v[4:5] op_sel_hi:[0,1]
	v_pk_mul_f32 v[2:3], v[34:35], v[2:3] op_sel_hi:[0,1]
	v_pk_fma_f32 v[2:3], v[152:153], v[100:101], v[2:3] op_sel_hi:[1,0,1]
	v_pk_fma_f32 v[4:5], v[150:151], v[100:101], v[4:5] op_sel_hi:[1,0,1]
	v_pk_fma_f32 v[2:3], v[36:37], v[6:7], v[2:3] op_sel_hi:[0,1,1]
	v_pk_fma_f32 v[4:5], v[36:37], v[8:9], v[4:5] op_sel_hi:[0,1,1]
	v_mov_b32_e32 v40, v35
	v_pk_fma_f32 v[2:3], v[38:39], v[10:11], v[2:3] op_sel_hi:[0,1,1]
	v_pk_fma_f32 v[4:5], v[38:39], v[12:13], v[4:5] op_sel_hi:[0,1,1]
	v_add_f32_e32 v134, v38, v40
	v_pk_fma_f32 v[138:139], v[40:41], v[16:17], v[4:5] op_sel_hi:[0,1,1]
	v_pk_fma_f32 v[140:141], v[40:41], v[14:15], v[2:3] op_sel_hi:[0,1,1]
	s_add_i32 s0, s8, 0x1000
	buffer_load_dwordx4 v[34:37], v161, s[12:15], s0 offen nt
	buffer_load_dwordx4 v[2:5], v161, s[4:7], s0 offen nt
	s_add_i32 s0, s3, 64
	buffer_load_dword v168, v162, s[16:19], s0 offen
	s_add_i32 s0, s8, 0x1400
	buffer_load_dwordx4 v[42:45], v161, s[12:15], s0 offen nt
	buffer_load_dwordx4 v[6:9], v161, s[4:7], s0 offen nt
	s_add_i32 s0, s3, 0x50
	buffer_load_dword v164, v162, s[16:19], s0 offen
	s_add_i32 s0, s8, 0x1800
	buffer_load_dwordx4 v[38:41], v161, s[12:15], s0 offen nt
	buffer_load_dwordx4 v[10:13], v161, s[4:7], s0 offen nt
	s_add_i32 s0, s3, 0x60
	buffer_load_dword v165, v162, s[16:19], s0 offen
	s_add_i32 s0, s8, 0x1c00
	buffer_load_dwordx4 v[46:49], v161, s[12:15], s0 offen nt
	buffer_load_dwordx4 v[14:17], v161, s[4:7], s0 offen nt
	s_add_i32 s0, s3, 0x70
	buffer_load_dword v166, v162, s[16:19], s0 offen
	v_pk_mul_f32 v[130:131], v[116:117], v[84:85]
	s_waitcnt vmcnt(24)
	v_add_f32_e32 v135, v101, v172
	v_pk_fma_f32 v[130:131], v[114:115], v[82:83], v[130:131]
	v_add_f32_e32 v137, v135, v145
	v_add_f32_e32 v98, v130, v131
	v_pk_mul_f32 v[130:131], v[116:117], v[88:89]
	v_add_f32_e32 v152, v137, v143
	v_pk_fma_f32 v[130:131], v[114:115], v[86:87], v[130:131]
	v_add_f32_dpp v98, v98, v98 quad_perm:[1,0,3,2] row_mask:0xf bank_mask:0xf bound_ctrl:1
	v_add_f32_e32 v130, v130, v131
	s_nop 0
	v_add_f32_dpp v98, v98, v98 quad_perm:[2,3,0,1] row_mask:0xf bank_mask:0xf bound_ctrl:1
	v_add_f32_dpp v130, v130, v130 quad_perm:[1,0,3,2] row_mask:0xf bank_mask:0xf bound_ctrl:1
	s_nop 0
	v_add_f32_dpp v98, v98, v98 row_half_mirror row_mask:0xf bank_mask:0xf bound_ctrl:1
	v_add_f32_dpp v130, v130, v130 quad_perm:[2,3,0,1] row_mask:0xf bank_mask:0xf bound_ctrl:1
	s_nop 0
	v_add_f32_dpp v98, v98, v98 row_mirror row_mask:0xf bank_mask:0xf bound_ctrl:1
	v_add_f32_dpp v130, v130, v130 row_half_mirror row_mask:0xf bank_mask:0xf bound_ctrl:1
	v_fmac_f32_e32 v98, 0x3fb8aa3b, v152
	s_nop 0
	v_add_f32_dpp v132, v130, v130 row_mirror row_mask:0xf bank_mask:0xf bound_ctrl:1
	v_pk_mul_f32 v[130:131], v[116:117], v[92:93]
	v_fmac_f32_e32 v132, 0x3fb8aa3b, v137
	v_pk_fma_f32 v[130:131], v[114:115], v[90:91], v[130:131]
	s_nop 0
	v_add_f32_e32 v130, v130, v131
	s_nop 1
	v_add_f32_dpp v130, v130, v130 quad_perm:[1,0,3,2] row_mask:0xf bank_mask:0xf bound_ctrl:1
	s_nop 1
	v_add_f32_dpp v130, v130, v130 quad_perm:[2,3,0,1] row_mask:0xf bank_mask:0xf bound_ctrl:1
	s_nop 1
	v_add_f32_dpp v130, v130, v130 row_half_mirror row_mask:0xf bank_mask:0xf bound_ctrl:1
	s_nop 1
	v_add_f32_dpp v133, v130, v130 row_mirror row_mask:0xf bank_mask:0xf bound_ctrl:1
	v_pk_mul_f32 v[130:131], v[116:117], v[96:97]
	v_fmac_f32_e32 v133, 0x3fb8aa3b, v135
	v_pk_fma_f32 v[130:131], v[114:115], v[94:95], v[130:131]
	s_nop 0
	v_add_f32_e32 v130, v130, v131
	s_nop 1
	v_add_f32_dpp v130, v130, v130 quad_perm:[1,0,3,2] row_mask:0xf bank_mask:0xf bound_ctrl:1
	s_nop 1
	v_add_f32_dpp v130, v130, v130 quad_perm:[2,3,0,1] row_mask:0xf bank_mask:0xf bound_ctrl:1
	s_nop 1
	v_add_f32_dpp v130, v130, v130 row_half_mirror row_mask:0xf bank_mask:0xf bound_ctrl:1
	s_nop 1
	v_add_f32_dpp v131, v130, v130 row_mirror row_mask:0xf bank_mask:0xf bound_ctrl:1
	v_fmac_f32_e32 v131, 0x3fb8aa3b, v101
	v_max_f32_e32 v130, v98, v132
	v_max_f32_e32 v143, v133, v131
	v_max3_f32 v151, v125, v130, v143
	v_sub_f32_e32 v125, v125, v151
	v_sub_f32_e32 v98, v98, v151
	v_exp_f32_e32 v125, v125
	s_nop 0
	v_mov_b32_e32 v176, v125
	v_exp_f32_e32 v98, v98
	v_sub_f32_e32 v125, v132, v151
	v_pk_mul_f32 v[180:181], v[98:99], v[66:67] op_sel_hi:[0,1]
	v_pk_fma_f32 v[156:157], v[156:157], v[176:177], v[180:181] op_sel_hi:[1,0,1]
	v_exp_f32_e32 v125, v125
	s_nop 0
	v_mov_b32_e32 v130, v125
	v_sub_f32_e32 v125, v133, v151
	v_add_f32_e32 v133, v98, v130
	v_exp_f32_e32 v125, v125
	s_nop 0
	v_mov_b32_e32 v145, v125
	v_sub_f32_e32 v125, v131, v151
	v_mul_f32_e32 v132, v175, v120
	v_exp_f32_e32 v125, v125
	s_nop 0
	v_mov_b32_e32 v143, v125
	v_pk_add_f32 v[178:179], v[144:145], v[142:143]
	s_nop 0
	v_pk_add_f32 v[178:179], v[132:133], v[178:179]
	v_pk_mul_f32 v[132:133], v[98:99], v[68:69] op_sel_hi:[0,1]
	v_pk_fma_f32 v[132:133], v[154:155], v[176:177], v[132:133] op_sel_hi:[1,0,1]
	v_mov_b32_e32 v98, v145
	v_pk_fma_f32 v[132:133], v[130:131], v[72:73], v[132:133] op_sel_hi:[0,1,1]
	v_pk_fma_f32 v[130:131], v[130:131], v[70:71], v[156:157] op_sel_hi:[0,1,1]
	v_pk_fma_f32 v[144:145], v[98:99], v[74:75], v[130:131] op_sel_hi:[0,1,1]
	v_pk_fma_f32 v[130:131], v[98:99], v[76:77], v[132:133] op_sel_hi:[0,1,1]
	v_mov_b32_e32 v98, v143
	v_pk_fma_f32 v[130:131], v[98:99], v[80:81], v[130:131] op_sel_hi:[0,1,1]
	v_pk_fma_f32 v[132:133], v[98:99], v[78:79], v[144:145] op_sel_hi:[0,1,1]
	v_pk_mul_f32 v[142:143], v[112:113], v[84:85]
	s_nop 0
	v_pk_fma_f32 v[142:143], v[110:111], v[82:83], v[142:143]
	s_nop 0
	v_add_f32_e32 v98, v142, v143
	v_pk_mul_f32 v[142:143], v[112:113], v[88:89]
	s_nop 0
	v_pk_fma_f32 v[142:143], v[110:111], v[86:87], v[142:143]
	v_add_f32_dpp v98, v98, v98 quad_perm:[1,0,3,2] row_mask:0xf bank_mask:0xf bound_ctrl:1
	v_add_f32_e32 v120, v142, v143
	v_pk_mul_f32 v[142:143], v[112:113], v[92:93]
	v_add_f32_dpp v98, v98, v98 quad_perm:[2,3,0,1] row_mask:0xf bank_mask:0xf bound_ctrl:1
	v_pk_fma_f32 v[142:143], v[110:111], v[90:91], v[142:143]
	v_add_f32_dpp v120, v120, v120 quad_perm:[1,0,3,2] row_mask:0xf bank_mask:0xf bound_ctrl:1
	v_add_f32_e32 v125, v142, v143
	v_pk_mul_f32 v[142:143], v[112:113], v[96:97]
	v_add_f32_dpp v120, v120, v120 quad_perm:[2,3,0,1] row_mask:0xf bank_mask:0xf bound_ctrl:1
	v_pk_fma_f32 v[142:143], v[110:111], v[94:95], v[142:143]
	v_add_f32_dpp v125, v125, v125 quad_perm:[1,0,3,2] row_mask:0xf bank_mask:0xf bound_ctrl:1
	v_add_f32_e32 v142, v142, v143
	v_add_f32_dpp v98, v98, v98 row_half_mirror row_mask:0xf bank_mask:0xf bound_ctrl:1
	v_add_f32_dpp v125, v125, v125 quad_perm:[2,3,0,1] row_mask:0xf bank_mask:0xf bound_ctrl:1
	v_add_f32_dpp v142, v142, v142 quad_perm:[1,0,3,2] row_mask:0xf bank_mask:0xf bound_ctrl:1
	v_add_f32_dpp v120, v120, v120 row_half_mirror row_mask:0xf bank_mask:0xf bound_ctrl:1
	v_add_f32_dpp v125, v125, v125 row_half_mirror row_mask:0xf bank_mask:0xf bound_ctrl:1
	v_add_f32_dpp v142, v142, v142 quad_perm:[2,3,0,1] row_mask:0xf bank_mask:0xf bound_ctrl:1
	v_add_f32_dpp v98, v98, v98 row_mirror row_mask:0xf bank_mask:0xf bound_ctrl:1
	v_add_f32_dpp v120, v120, v120 row_mirror row_mask:0xf bank_mask:0xf bound_ctrl:1
	v_add_f32_dpp v142, v142, v142 row_half_mirror row_mask:0xf bank_mask:0xf bound_ctrl:1
	v_add_f32_dpp v125, v125, v125 row_mirror row_mask:0xf bank_mask:0xf bound_ctrl:1
	v_fmac_f32_e32 v98, 0x3fb8aa3b, v152
	v_add_f32_dpp v145, v142, v142 row_mirror row_mask:0xf bank_mask:0xf bound_ctrl:1
	v_fmac_f32_e32 v120, 0x3fb8aa3b, v137
	v_fmac_f32_e32 v125, 0x3fb8aa3b, v135
	v_fmac_f32_e32 v145, 0x3fb8aa3b, v101
	v_max_f32_e32 v142, v98, v120
	v_max_f32_e32 v143, v125, v145
	v_max3_f32 v150, v123, v142, v143
	v_sub_f32_e32 v123, v123, v150
	v_sub_f32_e32 v98, v98, v150
	v_exp_f32_e32 v123, v123
	s_nop 0
	v_mov_b32_e32 v177, v123
	v_exp_f32_e32 v98, v98
	s_nop 0
	v_mov_b32_e32 v142, v98
	v_sub_f32_e32 v98, v120, v150
	v_exp_f32_e32 v98, v98
	s_nop 0
	v_mov_b32_e32 v144, v98
	v_sub_f32_e32 v98, v125, v150
	v_exp_f32_e32 v98, v98
	s_nop 0
	v_mov_b32_e32 v143, v98
	v_sub_f32_e32 v98, v145, v150
	v_pk_mul_f32 v[156:157], v[142:143], v[66:67] op_sel_hi:[0,1]
	v_exp_f32_e32 v98, v98
	s_nop 0
	v_mov_b32_e32 v145, v98
	v_pk_add_f32 v[154:155], v[142:143], v[144:145]
	v_mov_b32_e32 v98, v178
	v_pk_add_f32 v[154:155], v[154:155], v[154:155] op_sel_hi:[0,1]
	v_mov_b32_e32 v154, v179
	v_pk_fma_f32 v[98:99], v[98:99], v[176:177], v[154:155]
	v_pk_mul_f32 v[154:155], v[142:143], v[68:69] op_sel_hi:[0,1]
	v_mov_b32_e32 v120, v177
	v_pk_fma_f32 v[128:129], v[128:129], v[120:121], v[156:157] op_sel_hi:[1,0,1]
	v_pk_fma_f32 v[126:127], v[126:127], v[120:121], v[154:155] op_sel_hi:[1,0,1]
	v_pk_fma_f32 v[128:129], v[144:145], v[70:71], v[128:129] op_sel_hi:[0,1,1]
	v_pk_fma_f32 v[126:127], v[144:145], v[72:73], v[126:127] op_sel_hi:[0,1,1]
	v_mov_b32_e32 v120, v143
	v_pk_fma_f32 v[128:129], v[120:121], v[74:75], v[128:129] op_sel_hi:[0,1,1]
	v_pk_fma_f32 v[126:127], v[120:121], v[76:77], v[126:127] op_sel_hi:[0,1,1]
	v_mov_b32_e32 v120, v145
	v_pk_fma_f32 v[126:127], v[120:121], v[80:81], v[126:127] op_sel_hi:[0,1,1]
	v_pk_fma_f32 v[128:129], v[120:121], v[78:79], v[128:129] op_sel_hi:[0,1,1]
	v_pk_mul_f32 v[142:143], v[108:109], v[84:85]
	v_mul_f32_e32 v156, v173, v118
	v_pk_fma_f32 v[142:143], v[106:107], v[82:83], v[142:143]
	s_nop 0
	v_add_f32_e32 v120, v142, v143
	v_pk_mul_f32 v[142:143], v[108:109], v[88:89]
	s_nop 0
	v_add_f32_dpp v120, v120, v120 quad_perm:[1,0,3,2] row_mask:0xf bank_mask:0xf bound_ctrl:1
	v_pk_fma_f32 v[142:143], v[106:107], v[86:87], v[142:143]
	s_nop 0
	v_add_f32_dpp v120, v120, v120 quad_perm:[2,3,0,1] row_mask:0xf bank_mask:0xf bound_ctrl:1
	s_nop 1
	v_add_f32_dpp v120, v120, v120 row_half_mirror row_mask:0xf bank_mask:0xf bound_ctrl:1
	s_nop 1
	v_add_f32_dpp v123, v120, v120 row_mirror row_mask:0xf bank_mask:0xf bound_ctrl:1
	v_add_f32_e32 v120, v142, v143
	v_pk_mul_f32 v[142:143], v[108:109], v[92:93]
	v_fmac_f32_e32 v123, 0x3fb8aa3b, v152
	v_add_f32_dpp v120, v120, v120 quad_perm:[1,0,3,2] row_mask:0xf bank_mask:0xf bound_ctrl:1
	v_pk_fma_f32 v[142:143], v[106:107], v[90:91], v[142:143]
	s_nop 0
	v_add_f32_dpp v120, v120, v120 quad_perm:[2,3,0,1] row_mask:0xf bank_mask:0xf bound_ctrl:1
	s_nop 1
	v_add_f32_dpp v120, v120, v120 row_half_mirror row_mask:0xf bank_mask:0xf bound_ctrl:1
	s_nop 1
	v_add_f32_dpp v125, v120, v120 row_mirror row_mask:0xf bank_mask:0xf bound_ctrl:1
	v_add_f32_e32 v120, v142, v143
	v_pk_mul_f32 v[142:143], v[108:109], v[96:97]
	v_fmac_f32_e32 v125, 0x3fb8aa3b, v137
	v_add_f32_dpp v120, v120, v120 quad_perm:[1,0,3,2] row_mask:0xf bank_mask:0xf bound_ctrl:1
	v_pk_fma_f32 v[142:143], v[106:107], v[94:95], v[142:143]
	s_nop 0
	v_add_f32_dpp v120, v120, v120 quad_perm:[2,3,0,1] row_mask:0xf bank_mask:0xf bound_ctrl:1
	s_nop 1
	v_add_f32_dpp v120, v120, v120 row_half_mirror row_mask:0xf bank_mask:0xf bound_ctrl:1
	s_nop 1
	v_add_f32_dpp v145, v120, v120 row_mirror row_mask:0xf bank_mask:0xf bound_ctrl:1
	v_add_f32_e32 v120, v142, v143
	v_fmac_f32_e32 v145, 0x3fb8aa3b, v135
	s_nop 0
	v_add_f32_dpp v120, v120, v120 quad_perm:[1,0,3,2] row_mask:0xf bank_mask:0xf bound_ctrl:1
	s_nop 1
	v_add_f32_dpp v120, v120, v120 quad_perm:[2,3,0,1] row_mask:0xf bank_mask:0xf bound_ctrl:1
	s_nop 1
	v_add_f32_dpp v120, v120, v120 row_half_mirror row_mask:0xf bank_mask:0xf bound_ctrl:1
	s_nop 1
	v_add_f32_dpp v143, v120, v120 row_mirror row_mask:0xf bank_mask:0xf bound_ctrl:1
	v_fmac_f32_e32 v143, 0x3fb8aa3b, v101
	v_max_f32_e32 v120, v123, v125
	v_max_f32_e32 v142, v145, v143
	v_max3_f32 v144, v121, v120, v142
	v_sub_f32_e32 v120, v121, v144
	v_exp_f32_e32 v120, v120
	v_sub_f32_e32 v121, v123, v144
	v_exp_f32_e32 v121, v121
	s_nop 0
	v_mov_b32_e32 v142, v121
	v_sub_f32_e32 v121, v125, v144
	v_exp_f32_e32 v121, v121
	s_nop 0
	v_mov_b32_e32 v154, v121
	v_sub_f32_e32 v121, v145, v144
	v_add_f32_e32 v157, v142, v154
	v_exp_f32_e32 v121, v121
	s_nop 0
	v_mov_b32_e32 v125, v121
	v_sub_f32_e32 v121, v143, v144
	v_mov_b32_e32 v118, v125
	v_exp_f32_e32 v121, v121
	s_nop 0
	v_mov_b32_e32 v123, v121
	v_pk_add_f32 v[172:173], v[124:125], v[122:123]
	s_nop 0
	v_pk_add_f32 v[156:157], v[156:157], v[172:173]
	v_pk_mul_f32 v[172:173], v[142:143], v[68:69] op_sel_hi:[0,1]
	v_pk_mul_f32 v[142:143], v[142:143], v[66:67] op_sel_hi:[0,1]
	v_pk_fma_f32 v[142:143], v[148:149], v[120:121], v[142:143] op_sel_hi:[1,0,1]
	v_pk_fma_f32 v[146:147], v[146:147], v[120:121], v[172:173] op_sel_hi:[1,0,1]
	v_pk_fma_f32 v[142:143], v[154:155], v[70:71], v[142:143] op_sel_hi:[0,1,1]
	v_pk_fma_f32 v[146:147], v[154:155], v[72:73], v[146:147] op_sel_hi:[0,1,1]
	v_pk_fma_f32 v[124:125], v[118:119], v[74:75], v[142:143] op_sel_hi:[0,1,1]
	v_pk_fma_f32 v[142:143], v[118:119], v[76:77], v[146:147] op_sel_hi:[0,1,1]
	v_mov_b32_e32 v118, v123
	v_pk_fma_f32 v[122:123], v[118:119], v[80:81], v[142:143] op_sel_hi:[0,1,1]
	v_pk_fma_f32 v[124:125], v[118:119], v[78:79], v[124:125] op_sel_hi:[0,1,1]
	v_pk_mul_f32 v[84:85], v[104:105], v[84:85]
	s_nop 0
	v_pk_fma_f32 v[82:83], v[102:103], v[82:83], v[84:85]
	s_nop 0
	v_add_f32_e32 v82, v82, v83
	s_nop 1
	v_add_f32_dpp v82, v82, v82 quad_perm:[1,0,3,2] row_mask:0xf bank_mask:0xf bound_ctrl:1
	s_nop 1
	v_add_f32_dpp v82, v82, v82 quad_perm:[2,3,0,1] row_mask:0xf bank_mask:0xf bound_ctrl:1
	s_nop 1
	v_add_f32_dpp v82, v82, v82 row_half_mirror row_mask:0xf bank_mask:0xf bound_ctrl:1
	s_nop 1
	v_add_f32_dpp v84, v82, v82 row_mirror row_mask:0xf bank_mask:0xf bound_ctrl:1
	v_pk_mul_f32 v[82:83], v[104:105], v[88:89]
	v_fmac_f32_e32 v84, 0x3fb8aa3b, v152
	v_pk_fma_f32 v[82:83], v[102:103], v[86:87], v[82:83]
	s_nop 0
	v_add_f32_e32 v82, v82, v83
	s_nop 1
	v_add_f32_dpp v82, v82, v82 quad_perm:[1,0,3,2] row_mask:0xf bank_mask:0xf bound_ctrl:1
	s_nop 1
	v_add_f32_dpp v82, v82, v82 quad_perm:[2,3,0,1] row_mask:0xf bank_mask:0xf bound_ctrl:1
	s_nop 1
	v_add_f32_dpp v82, v82, v82 row_half_mirror row_mask:0xf bank_mask:0xf bound_ctrl:1
	s_nop 1
	v_add_f32_dpp v85, v82, v82 row_mirror row_mask:0xf bank_mask:0xf bound_ctrl:1
	v_pk_mul_f32 v[82:83], v[104:105], v[92:93]
	v_fmac_f32_e32 v85, 0x3fb8aa3b, v137
	v_pk_fma_f32 v[82:83], v[102:103], v[90:91], v[82:83]
	s_nop 0
	v_add_f32_e32 v82, v82, v83
	s_nop 1
	v_add_f32_dpp v82, v82, v82 quad_perm:[1,0,3,2] row_mask:0xf bank_mask:0xf bound_ctrl:1
	s_nop 1
	v_add_f32_dpp v82, v82, v82 quad_perm:[2,3,0,1] row_mask:0xf bank_mask:0xf bound_ctrl:1
	s_nop 1
	v_add_f32_dpp v82, v82, v82 row_half_mirror row_mask:0xf bank_mask:0xf bound_ctrl:1
	s_nop 1
	v_add_f32_dpp v86, v82, v82 row_mirror row_mask:0xf bank_mask:0xf bound_ctrl:1
	v_pk_mul_f32 v[82:83], v[104:105], v[96:97]
	v_fmac_f32_e32 v86, 0x3fb8aa3b, v135
	v_pk_fma_f32 v[82:83], v[102:103], v[94:95], v[82:83]
	s_nop 0
	v_add_f32_e32 v82, v82, v83
	s_nop 1
	v_add_f32_dpp v82, v82, v82 quad_perm:[1,0,3,2] row_mask:0xf bank_mask:0xf bound_ctrl:1
	s_nop 1
	v_add_f32_dpp v82, v82, v82 quad_perm:[2,3,0,1] row_mask:0xf bank_mask:0xf bound_ctrl:1
	s_nop 1
	v_add_f32_dpp v82, v82, v82 row_half_mirror row_mask:0xf bank_mask:0xf bound_ctrl:1
	s_nop 1
	v_add_f32_dpp v83, v82, v82 row_mirror row_mask:0xf bank_mask:0xf bound_ctrl:1
	v_fmac_f32_e32 v83, 0x3fb8aa3b, v101
	v_max_f32_e32 v82, v84, v85
	v_max_f32_e32 v87, v86, v83
	v_max3_f32 v142, v119, v82, v87
	v_sub_f32_e32 v82, v119, v142
	v_sub_f32_e32 v83, v83, v142
	v_exp_f32_e32 v82, v82
	s_nop 0
	v_mov_b32_e32 v121, v82
	v_sub_f32_e32 v82, v84, v142
	v_exp_f32_e32 v82, v82
	v_sub_f32_e32 v84, v85, v142
	v_exp_f32_e32 v84, v84
	v_sub_f32_e32 v85, v86, v142
	v_add_f32_e32 v87, v82, v84
	v_exp_f32_e32 v85, v85
	s_nop 0
	v_mov_b32_e32 v137, v85
	v_exp_f32_e32 v83, v83
	v_mul_f32_e32 v86, v174, v100
	v_mov_b32_e32 v135, v83
	v_pk_mul_f32 v[68:69], v[82:83], v[68:69] op_sel_hi:[0,1]
	v_pk_mul_f32 v[66:67], v[82:83], v[66:67] op_sel_hi:[0,1]
	v_mov_b32_e32 v82, v121
	v_pk_add_f32 v[88:89], v[136:137], v[134:135]
	v_pk_fma_f32 v[66:67], v[140:141], v[82:83], v[66:67] op_sel_hi:[1,0,1]
	v_pk_fma_f32 v[68:69], v[138:139], v[82:83], v[68:69] op_sel_hi:[1,0,1]
	v_pk_add_f32 v[86:87], v[86:87], v[88:89]
	v_pk_fma_f32 v[68:69], v[84:85], v[72:73], v[68:69] op_sel_hi:[0,1,1]
	v_pk_fma_f32 v[66:67], v[84:85], v[70:71], v[66:67] op_sel_hi:[0,1,1]
	v_mov_b32_e32 v70, v137
	v_mov_b32_e32 v88, v156
	v_mov_b32_e32 v89, v86
	v_mov_b32_e32 v86, v157
	v_pk_fma_f32 v[66:67], v[70:71], v[74:75], v[66:67] op_sel_hi:[0,1,1]
	v_pk_fma_f32 v[68:69], v[70:71], v[76:77], v[68:69] op_sel_hi:[0,1,1]
	v_mov_b32_e32 v70, v135
	v_pk_fma_f32 v[100:101], v[88:89], v[120:121], v[86:87]
	v_pk_fma_f32 v[120:121], v[70:71], v[80:81], v[68:69] op_sel_hi:[0,1,1]
	v_pk_fma_f32 v[118:119], v[70:71], v[78:79], v[66:67] op_sel_hi:[0,1,1]
	v_add_f32_e32 v146, v152, v163
	s_add_i32 s0, s8, 0x400
	buffer_load_dwordx4 v[82:85], v161, s[12:15], s8 offen nt
	buffer_load_dwordx4 v[66:69], v161, s[4:7], s8 offen nt
	buffer_load_dword v163, v162, s[16:19], s3 offen
	buffer_load_dwordx4 v[86:89], v161, s[12:15], s0 offen nt
	buffer_load_dwordx4 v[70:73], v161, s[4:7], s0 offen nt
	s_add_i32 s0, s3, 16
	buffer_load_dword v143, v162, s[16:19], s0 offen
	s_add_i32 s0, s8, 0x800
	buffer_load_dwordx4 v[90:93], v161, s[12:15], s0 offen nt
	buffer_load_dwordx4 v[74:77], v161, s[4:7], s0 offen nt
	s_add_i32 s0, s3, 32
	buffer_load_dword v145, v162, s[16:19], s0 offen
	s_add_i32 s0, s8, 0xc00
	buffer_load_dwordx4 v[94:97], v161, s[12:15], s0 offen nt
	buffer_load_dwordx4 v[78:81], v161, s[4:7], s0 offen nt
	s_add_i32 s0, s3, 48
	buffer_load_dword v172, v162, s[16:19], s0 offen
	s_add_i32 s2, s2, -12
	s_addk_i32 s3, 0xff40
	s_addk_i32 s8, 0xd000
	s_cmp_lt_u32 s2, 24
	s_cbranch_scc0 .LBB0_323
	s_waitcnt vmcnt(7)
	v_pk_mul_f32 v[72:73], v[116:117], v[52:53]
	v_add_f32_e32 v67, v146, v171
	v_pk_fma_f32 v[72:73], v[114:115], v[50:51], v[72:73]
	v_add_f32_e32 v69, v67, v170
	v_add_f32_e32 v66, v72, v73
	v_pk_mul_f32 v[72:73], v[116:117], v[60:61]
	v_add_f32_e32 v71, v69, v169
	v_add_f32_dpp v66, v66, v66 quad_perm:[1,0,3,2] row_mask:0xf bank_mask:0xf bound_ctrl:1
	v_pk_fma_f32 v[72:73], v[114:115], v[58:59], v[72:73]
	s_nop 0
	v_add_f32_dpp v66, v66, v66 quad_perm:[2,3,0,1] row_mask:0xf bank_mask:0xf bound_ctrl:1
	s_nop 1
	v_add_f32_dpp v66, v66, v66 row_half_mirror row_mask:0xf bank_mask:0xf bound_ctrl:1
	s_nop 1
	v_add_f32_dpp v68, v66, v66 row_mirror row_mask:0xf bank_mask:0xf bound_ctrl:1
	v_add_f32_e32 v66, v72, v73
	v_pk_mul_f32 v[72:73], v[116:117], v[56:57]
	v_fmac_f32_e32 v68, 0x3fb8aa3b, v71
	v_add_f32_dpp v66, v66, v66 quad_perm:[1,0,3,2] row_mask:0xf bank_mask:0xf bound_ctrl:1
	v_pk_fma_f32 v[72:73], v[114:115], v[54:55], v[72:73]
	s_nop 0
	v_add_f32_dpp v66, v66, v66 quad_perm:[2,3,0,1] row_mask:0xf bank_mask:0xf bound_ctrl:1
	s_nop 1
	v_add_f32_dpp v66, v66, v66 row_half_mirror row_mask:0xf bank_mask:0xf bound_ctrl:1
	s_nop 1
	v_add_f32_dpp v70, v66, v66 row_mirror row_mask:0xf bank_mask:0xf bound_ctrl:1
	v_add_f32_e32 v66, v72, v73
	v_pk_mul_f32 v[72:73], v[116:117], v[64:65]
	v_fmac_f32_e32 v70, 0x3fb8aa3b, v69
	v_add_f32_dpp v66, v66, v66 quad_perm:[1,0,3,2] row_mask:0xf bank_mask:0xf bound_ctrl:1
	v_pk_fma_f32 v[72:73], v[114:115], v[62:63], v[72:73]
	s_nop 0
	v_add_f32_dpp v66, v66, v66 quad_perm:[2,3,0,1] row_mask:0xf bank_mask:0xf bound_ctrl:1
	s_nop 1
	v_add_f32_dpp v66, v66, v66 row_half_mirror row_mask:0xf bank_mask:0xf bound_ctrl:1
	s_waitcnt vmcnt(4)
	s_nop 0
	v_add_f32_dpp v74, v66, v66 row_mirror row_mask:0xf bank_mask:0xf bound_ctrl:1
	v_add_f32_e32 v66, v72, v73
	v_fmac_f32_e32 v74, 0x3fb8aa3b, v67
	s_nop 0
	v_add_f32_dpp v66, v66, v66 quad_perm:[1,0,3,2] row_mask:0xf bank_mask:0xf bound_ctrl:1
	s_nop 1
	v_add_f32_dpp v66, v66, v66 quad_perm:[2,3,0,1] row_mask:0xf bank_mask:0xf bound_ctrl:1
	s_nop 1
	v_add_f32_dpp v66, v66, v66 row_half_mirror row_mask:0xf bank_mask:0xf bound_ctrl:1
	s_nop 1
	v_add_f32_dpp v73, v66, v66 row_mirror row_mask:0xf bank_mask:0xf bound_ctrl:1
	v_fmac_f32_e32 v73, 0x3fb8aa3b, v146
	v_max_f32_e32 v66, v68, v70
	v_max_f32_e32 v72, v74, v73
	s_waitcnt vmcnt(2)
	v_max3_f32 v96, v151, v66, v72
	v_sub_f32_e32 v66, v151, v96
	v_sub_f32_e32 v68, v68, v96
	v_sub_f32_e32 v70, v70, v96
	v_exp_f32_e32 v66, v66
	v_sub_f32_e32 v73, v73, v96
	v_exp_f32_e32 v68, v68
	v_exp_f32_e32 v70, v70
	v_pk_mul_f32 v[76:77], v[68:69], v[24:25] op_sel_hi:[0,1]
	s_waitcnt vmcnt(1)
	v_pk_mul_f32 v[78:79], v[68:69], v[22:23] op_sel_hi:[0,1]
	v_sub_f32_e32 v72, v74, v96
	v_pk_fma_f32 v[78:79], v[132:133], v[66:67], v[78:79] op_sel_hi:[1,0,1]
	v_pk_fma_f32 v[76:77], v[130:131], v[66:67], v[76:77] op_sel_hi:[1,0,1]
	v_exp_f32_e32 v72, v72
	v_pk_fma_f32 v[76:77], v[70:71], v[20:21], v[76:77] op_sel_hi:[0,1,1]
	v_exp_f32_e32 v73, v73
	v_pk_fma_f32 v[78:79], v[70:71], v[18:19], v[78:79] op_sel_hi:[0,1,1]
	v_mov_b32_e32 v74, v73
	v_pk_fma_f32 v[78:79], v[72:73], v[26:27], v[78:79] op_sel_hi:[0,1,1]
	v_pk_fma_f32 v[76:77], v[72:73], v[28:29], v[76:77] op_sel_hi:[0,1,1]
	v_pk_fma_f32 v[90:91], v[74:75], v[32:33], v[76:77] op_sel_hi:[0,1,1]
	v_pk_fma_f32 v[92:93], v[74:75], v[30:31], v[78:79] op_sel_hi:[0,1,1]
	v_pk_mul_f32 v[76:77], v[112:113], v[52:53]
	s_nop 0
	v_pk_fma_f32 v[76:77], v[110:111], v[50:51], v[76:77]
	s_nop 0
	v_add_f32_e32 v73, v76, v77
	v_pk_mul_f32 v[76:77], v[112:113], v[60:61]
	s_nop 0
	v_pk_fma_f32 v[76:77], v[110:111], v[58:59], v[76:77]
	v_add_f32_dpp v73, v73, v73 quad_perm:[1,0,3,2] row_mask:0xf bank_mask:0xf bound_ctrl:1
	v_add_f32_e32 v75, v76, v77
	v_pk_mul_f32 v[76:77], v[112:113], v[56:57]
	v_add_f32_dpp v73, v73, v73 quad_perm:[2,3,0,1] row_mask:0xf bank_mask:0xf bound_ctrl:1
	v_pk_fma_f32 v[76:77], v[110:111], v[54:55], v[76:77]
	v_add_f32_dpp v75, v75, v75 quad_perm:[1,0,3,2] row_mask:0xf bank_mask:0xf bound_ctrl:1
	v_add_f32_e32 v76, v76, v77
	v_add_f32_dpp v73, v73, v73 row_half_mirror row_mask:0xf bank_mask:0xf bound_ctrl:1
	v_add_f32_dpp v75, v75, v75 quad_perm:[2,3,0,1] row_mask:0xf bank_mask:0xf bound_ctrl:1
	v_add_f32_dpp v76, v76, v76 quad_perm:[1,0,3,2] row_mask:0xf bank_mask:0xf bound_ctrl:1
	v_add_f32_dpp v73, v73, v73 row_mirror row_mask:0xf bank_mask:0xf bound_ctrl:1
	v_add_f32_dpp v75, v75, v75 row_half_mirror row_mask:0xf bank_mask:0xf bound_ctrl:1
	v_add_f32_dpp v76, v76, v76 quad_perm:[2,3,0,1] row_mask:0xf bank_mask:0xf bound_ctrl:1
	v_fmac_f32_e32 v73, 0x3fb8aa3b, v71
	v_add_f32_dpp v75, v75, v75 row_mirror row_mask:0xf bank_mask:0xf bound_ctrl:1
	v_add_f32_dpp v76, v76, v76 row_half_mirror row_mask:0xf bank_mask:0xf bound_ctrl:1
	v_fmac_f32_e32 v75, 0x3fb8aa3b, v69
	s_nop 0
	v_add_f32_dpp v79, v76, v76 row_mirror row_mask:0xf bank_mask:0xf bound_ctrl:1
	v_pk_mul_f32 v[76:77], v[112:113], v[64:65]
	v_fmac_f32_e32 v79, 0x3fb8aa3b, v67
	v_pk_fma_f32 v[76:77], v[110:111], v[62:63], v[76:77]
	s_nop 0
	v_add_f32_e32 v76, v76, v77
	s_nop 1
	v_add_f32_dpp v76, v76, v76 quad_perm:[1,0,3,2] row_mask:0xf bank_mask:0xf bound_ctrl:1
	s_nop 1
	v_add_f32_dpp v76, v76, v76 quad_perm:[2,3,0,1] row_mask:0xf bank_mask:0xf bound_ctrl:1
	s_nop 1
	v_add_f32_dpp v76, v76, v76 row_half_mirror row_mask:0xf bank_mask:0xf bound_ctrl:1
	s_nop 1
	v_add_f32_dpp v77, v76, v76 row_mirror row_mask:0xf bank_mask:0xf bound_ctrl:1
	v_fmac_f32_e32 v77, 0x3fb8aa3b, v146
	v_max_f32_e32 v76, v73, v75
	v_max_f32_e32 v78, v79, v77
	v_max3_f32 v136, v150, v76, v78
	v_sub_f32_e32 v76, v150, v136
	v_sub_f32_e32 v73, v73, v136
	v_exp_f32_e32 v76, v76
	v_exp_f32_e32 v73, v73
	s_nop 0
	v_mov_b32_e32 v78, v73
	v_sub_f32_e32 v73, v75, v136
	v_pk_mul_f32 v[86:87], v[78:79], v[24:25] op_sel_hi:[0,1]
	v_pk_mul_f32 v[88:89], v[78:79], v[22:23] op_sel_hi:[0,1]
	v_exp_f32_e32 v73, v73
	v_pk_fma_f32 v[88:89], v[128:129], v[76:77], v[88:89] op_sel_hi:[1,0,1]
	v_pk_fma_f32 v[86:87], v[126:127], v[76:77], v[86:87] op_sel_hi:[1,0,1]
	v_mov_b32_e32 v80, v73
	v_sub_f32_e32 v73, v79, v136
	v_pk_fma_f32 v[86:87], v[80:81], v[20:21], v[86:87] op_sel_hi:[0,1,1]
	v_pk_fma_f32 v[88:89], v[80:81], v[18:19], v[88:89] op_sel_hi:[0,1,1]
	v_exp_f32_e32 v73, v73
	s_nop 0
	v_mov_b32_e32 v82, v73
	v_sub_f32_e32 v73, v77, v136
	v_pk_fma_f32 v[88:89], v[82:83], v[26:27], v[88:89] op_sel_hi:[0,1,1]
	v_pk_fma_f32 v[86:87], v[82:83], v[28:29], v[86:87] op_sel_hi:[0,1,1]
	v_exp_f32_e32 v73, v73
	s_nop 0
	v_mov_b32_e32 v84, v73
	v_pk_fma_f32 v[86:87], v[84:85], v[32:33], v[86:87] op_sel_hi:[0,1,1]
	v_pk_fma_f32 v[88:89], v[84:85], v[30:31], v[88:89] op_sel_hi:[0,1,1]
	v_pk_mul_f32 v[94:95], v[108:109], v[52:53]
	v_pk_mul_f32 v[126:127], v[108:109], v[64:65]
	v_pk_fma_f32 v[94:95], v[106:107], v[50:51], v[94:95]
	v_pk_fma_f32 v[126:127], v[106:107], v[62:63], v[126:127]
	v_add_f32_e32 v73, v94, v95
	v_pk_mul_f32 v[94:95], v[108:109], v[60:61]
	s_nop 0
	v_add_f32_dpp v73, v73, v73 quad_perm:[1,0,3,2] row_mask:0xf bank_mask:0xf bound_ctrl:1
	v_pk_fma_f32 v[94:95], v[106:107], v[58:59], v[94:95]
	s_nop 0
	v_add_f32_dpp v73, v73, v73 quad_perm:[2,3,0,1] row_mask:0xf bank_mask:0xf bound_ctrl:1
	s_nop 1
	v_add_f32_dpp v79, v73, v73 row_half_mirror row_mask:0xf bank_mask:0xf bound_ctrl:1
	v_add_f32_e32 v73, v94, v95
	v_pk_mul_f32 v[94:95], v[108:109], v[56:57]
	v_mov_b32_dpp v81, v79 row_mirror row_mask:0xf bank_mask:0xf bound_ctrl:1
	v_add_f32_dpp v73, v73, v73 quad_perm:[1,0,3,2] row_mask:0xf bank_mask:0xf bound_ctrl:1
	v_pk_fma_f32 v[94:95], v[106:107], v[54:55], v[94:95]
	s_nop 0
	v_add_f32_dpp v73, v73, v73 quad_perm:[2,3,0,1] row_mask:0xf bank_mask:0xf bound_ctrl:1
	s_nop 1
	v_add_f32_dpp v83, v73, v73 row_half_mirror row_mask:0xf bank_mask:0xf bound_ctrl:1
	v_add_f32_e32 v73, v94, v95
	s_nop 0
	v_mov_b32_dpp v85, v83 row_mirror row_mask:0xf bank_mask:0xf bound_ctrl:1
	v_add_f32_dpp v73, v73, v73 quad_perm:[1,0,3,2] row_mask:0xf bank_mask:0xf bound_ctrl:1
	s_nop 1
	v_add_f32_dpp v73, v73, v73 quad_perm:[2,3,0,1] row_mask:0xf bank_mask:0xf bound_ctrl:1
	s_nop 1
	v_add_f32_dpp v95, v73, v73 row_half_mirror row_mask:0xf bank_mask:0xf bound_ctrl:1
	v_add_f32_e32 v73, v126, v127
	s_nop 0
	v_mov_b32_dpp v97, v95 row_mirror row_mask:0xf bank_mask:0xf bound_ctrl:1
	v_add_f32_dpp v73, v73, v73 quad_perm:[1,0,3,2] row_mask:0xf bank_mask:0xf bound_ctrl:1
	s_nop 1
	v_add_f32_dpp v73, v73, v73 quad_perm:[2,3,0,1] row_mask:0xf bank_mask:0xf bound_ctrl:1
	s_nop 1
	v_add_f32_dpp v126, v73, v73 row_half_mirror row_mask:0xf bank_mask:0xf bound_ctrl:1
	s_nop 1
	v_mov_b32_dpp v127, v126 row_mirror row_mask:0xf bank_mask:0xf bound_ctrl:1
	v_pk_mul_f32 v[52:53], v[104:105], v[52:53]
	s_nop 0
	v_pk_fma_f32 v[50:51], v[102:103], v[50:51], v[52:53]
	s_nop 0
	v_add_f32_e32 v50, v50, v51
	s_nop 1
	v_add_f32_dpp v50, v50, v50 quad_perm:[1,0,3,2] row_mask:0xf bank_mask:0xf bound_ctrl:1
	s_nop 1
	v_add_f32_dpp v50, v50, v50 quad_perm:[2,3,0,1] row_mask:0xf bank_mask:0xf bound_ctrl:1
	s_nop 1
	v_add_f32_dpp v73, v50, v50 row_half_mirror row_mask:0xf bank_mask:0xf bound_ctrl:1
	v_pk_mul_f32 v[50:51], v[104:105], v[60:61]
	s_nop 0
	v_pk_fma_f32 v[50:51], v[102:103], v[58:59], v[50:51]
	v_mov_b32_dpp v75, v73 row_mirror row_mask:0xf bank_mask:0xf bound_ctrl:1
	v_add_f32_e32 v50, v50, v51
	s_nop 1
	v_add_f32_dpp v50, v50, v50 quad_perm:[1,0,3,2] row_mask:0xf bank_mask:0xf bound_ctrl:1
	s_nop 1
	v_add_f32_dpp v50, v50, v50 quad_perm:[2,3,0,1] row_mask:0xf bank_mask:0xf bound_ctrl:1
	s_nop 1
	v_add_f32_dpp v59, v50, v50 row_half_mirror row_mask:0xf bank_mask:0xf bound_ctrl:1
	v_pk_mul_f32 v[50:51], v[104:105], v[56:57]
	s_nop 0
	v_pk_fma_f32 v[50:51], v[102:103], v[54:55], v[50:51]
	v_mov_b32_dpp v61, v59 row_mirror row_mask:0xf bank_mask:0xf bound_ctrl:1
	v_add_f32_e32 v50, v50, v51
	s_nop 1
	v_add_f32_dpp v50, v50, v50 quad_perm:[1,0,3,2] row_mask:0xf bank_mask:0xf bound_ctrl:1
	s_nop 1
	v_add_f32_dpp v50, v50, v50 quad_perm:[2,3,0,1] row_mask:0xf bank_mask:0xf bound_ctrl:1
	s_nop 1
	v_add_f32_dpp v57, v50, v50 row_half_mirror row_mask:0xf bank_mask:0xf bound_ctrl:1
	v_pk_mul_f32 v[50:51], v[104:105], v[64:65]
	s_nop 0
	v_pk_fma_f32 v[50:51], v[102:103], v[62:63], v[50:51]
	v_mov_b32_dpp v77, v57 row_mirror row_mask:0xf bank_mask:0xf bound_ctrl:1
	v_add_f32_e32 v50, v50, v51
	s_nop 1
	v_add_f32_dpp v50, v50, v50 quad_perm:[1,0,3,2] row_mask:0xf bank_mask:0xf bound_ctrl:1
	s_nop 1
	v_add_f32_dpp v50, v50, v50 quad_perm:[2,3,0,1] row_mask:0xf bank_mask:0xf bound_ctrl:1
	s_nop 1
	v_add_f32_dpp v63, v50, v50 row_half_mirror row_mask:0xf bank_mask:0xf bound_ctrl:1
	s_nop 1
	v_mov_b32_dpp v65, v63 row_mirror row_mask:0xf bank_mask:0xf bound_ctrl:1
	v_add_f32_e32 v128, v71, v167
	v_pk_mul_f32 v[50:51], v[116:117], v[36:37]
	v_add_f32_e32 v129, v128, v166
	v_pk_fma_f32 v[50:51], v[114:115], v[34:35], v[50:51]
	v_add_f32_e32 v130, v129, v165
	v_add_f32_e32 v50, v50, v51
	v_add_f32_e32 v131, v130, v164
	s_nop 0
	v_add_f32_dpp v50, v50, v50 quad_perm:[1,0,3,2] row_mask:0xf bank_mask:0xf bound_ctrl:1
	s_nop 1
	v_add_f32_dpp v50, v50, v50 quad_perm:[2,3,0,1] row_mask:0xf bank_mask:0xf bound_ctrl:1
	s_nop 1
	v_add_f32_dpp v50, v50, v50 row_half_mirror row_mask:0xf bank_mask:0xf bound_ctrl:1
	s_nop 1
	v_add_f32_dpp v52, v50, v50 row_mirror row_mask:0xf bank_mask:0xf bound_ctrl:1
	v_pk_mul_f32 v[50:51], v[116:117], v[44:45]
	v_fmac_f32_e32 v52, 0x3fb8aa3b, v131
	v_pk_fma_f32 v[50:51], v[114:115], v[42:43], v[50:51]
	s_nop 0
	v_add_f32_e32 v50, v50, v51
	s_nop 1
	v_add_f32_dpp v50, v50, v50 quad_perm:[1,0,3,2] row_mask:0xf bank_mask:0xf bound_ctrl:1
	s_nop 1
	v_add_f32_dpp v50, v50, v50 quad_perm:[2,3,0,1] row_mask:0xf bank_mask:0xf bound_ctrl:1
	s_nop 1
	v_add_f32_dpp v50, v50, v50 row_half_mirror row_mask:0xf bank_mask:0xf bound_ctrl:1
	s_nop 1
	v_add_f32_dpp v53, v50, v50 row_mirror row_mask:0xf bank_mask:0xf bound_ctrl:1
	v_pk_mul_f32 v[50:51], v[116:117], v[40:41]
	v_fmac_f32_e32 v53, 0x3fb8aa3b, v130
	v_pk_fma_f32 v[50:51], v[114:115], v[38:39], v[50:51]
	s_nop 0
	v_add_f32_e32 v50, v50, v51
	s_nop 1
	v_add_f32_dpp v50, v50, v50 quad_perm:[1,0,3,2] row_mask:0xf bank_mask:0xf bound_ctrl:1
	s_nop 1
	v_add_f32_dpp v50, v50, v50 quad_perm:[2,3,0,1] row_mask:0xf bank_mask:0xf bound_ctrl:1
	s_nop 1
	v_add_f32_dpp v50, v50, v50 row_half_mirror row_mask:0xf bank_mask:0xf bound_ctrl:1
	s_nop 1
	v_add_f32_dpp v55, v50, v50 row_mirror row_mask:0xf bank_mask:0xf bound_ctrl:1
	v_pk_mul_f32 v[50:51], v[116:117], v[48:49]
	v_fmac_f32_e32 v55, 0x3fb8aa3b, v129
	v_pk_fma_f32 v[50:51], v[114:115], v[46:47], v[50:51]
	s_nop 0
	v_add_f32_e32 v50, v50, v51
	v_max_f32_e32 v51, v52, v53
	s_nop 0
	v_add_f32_dpp v50, v50, v50 quad_perm:[1,0,3,2] row_mask:0xf bank_mask:0xf bound_ctrl:1
	s_nop 1
	v_add_f32_dpp v50, v50, v50 quad_perm:[2,3,0,1] row_mask:0xf bank_mask:0xf bound_ctrl:1
	s_nop 1
	v_add_f32_dpp v50, v50, v50 row_half_mirror row_mask:0xf bank_mask:0xf bound_ctrl:1
	s_nop 1
	v_add_f32_dpp v50, v50, v50 row_mirror row_mask:0xf bank_mask:0xf bound_ctrl:1
	v_fmac_f32_e32 v50, 0x3fb8aa3b, v128
	v_max_f32_e32 v54, v55, v50
	v_max3_f32 v54, v96, v51, v54
	v_sub_f32_e32 v51, v96, v54
	v_sub_f32_e32 v50, v50, v54
	v_exp_f32_e32 v51, v51
	s_nop 0
	v_mov_b32_e32 v56, v51
	v_sub_f32_e32 v51, v52, v54
	v_exp_f32_e32 v51, v51
	s_nop 0
	v_mov_b32_e32 v58, v51
	v_sub_f32_e32 v51, v53, v54
	v_exp_f32_e32 v51, v51
	s_nop 0
	v_mov_b32_e32 v60, v51
	v_sub_f32_e32 v51, v55, v54
	v_exp_f32_e32 v51, v51
	s_nop 0
	v_mov_b32_e32 v62, v51
	v_exp_f32_e32 v50, v50
	v_pk_mul_f32 v[52:53], v[58:59], v[2:3] op_sel_hi:[0,1]
	v_pk_fma_f32 v[52:53], v[92:93], v[56:57], v[52:53] op_sel_hi:[1,0,1]
	v_mov_b32_e32 v64, v50
	v_pk_mul_f32 v[50:51], v[58:59], v[4:5] op_sel_hi:[0,1]
	v_pk_fma_f32 v[50:51], v[90:91], v[56:57], v[50:51] op_sel_hi:[1,0,1]
	v_pk_fma_f32 v[52:53], v[60:61], v[6:7], v[52:53] op_sel_hi:[0,1,1]
	v_pk_fma_f32 v[50:51], v[60:61], v[8:9], v[50:51] op_sel_hi:[0,1,1]
	v_pk_fma_f32 v[52:53], v[62:63], v[10:11], v[52:53] op_sel_hi:[0,1,1]
	v_pk_fma_f32 v[50:51], v[62:63], v[12:13], v[50:51] op_sel_hi:[0,1,1]
	v_pk_fma_f32 v[134:135], v[64:65], v[16:17], v[50:51] op_sel_hi:[0,1,1]
	v_pk_fma_f32 v[132:133], v[64:65], v[14:15], v[52:53] op_sel_hi:[0,1,1]
	v_pk_mul_f32 v[50:51], v[112:113], v[36:37]
	s_nop 0
	v_pk_fma_f32 v[50:51], v[110:111], v[34:35], v[50:51]
	s_nop 0
	v_add_f32_e32 v50, v50, v51
	s_nop 1
	v_add_f32_dpp v50, v50, v50 quad_perm:[1,0,3,2] row_mask:0xf bank_mask:0xf bound_ctrl:1
	s_nop 1
	v_add_f32_dpp v50, v50, v50 quad_perm:[2,3,0,1] row_mask:0xf bank_mask:0xf bound_ctrl:1
	s_nop 1
	v_add_f32_dpp v50, v50, v50 row_half_mirror row_mask:0xf bank_mask:0xf bound_ctrl:1
	s_nop 1
	v_add_f32_dpp v52, v50, v50 row_mirror row_mask:0xf bank_mask:0xf bound_ctrl:1
	v_pk_mul_f32 v[50:51], v[112:113], v[44:45]
	v_fmac_f32_e32 v52, 0x3fb8aa3b, v131
	v_pk_fma_f32 v[50:51], v[110:111], v[42:43], v[50:51]
	s_nop 0
	v_add_f32_e32 v50, v50, v51
	s_nop 1
	v_add_f32_dpp v50, v50, v50 quad_perm:[1,0,3,2] row_mask:0xf bank_mask:0xf bound_ctrl:1
	s_nop 1
	v_add_f32_dpp v50, v50, v50 quad_perm:[2,3,0,1] row_mask:0xf bank_mask:0xf bound_ctrl:1
	s_nop 1
	v_add_f32_dpp v50, v50, v50 row_half_mirror row_mask:0xf bank_mask:0xf bound_ctrl:1
	s_nop 1
	v_add_f32_dpp v53, v50, v50 row_mirror row_mask:0xf bank_mask:0xf bound_ctrl:1
	v_pk_mul_f32 v[50:51], v[112:113], v[40:41]
	v_fmac_f32_e32 v53, 0x3fb8aa3b, v130
	v_pk_fma_f32 v[50:51], v[110:111], v[38:39], v[50:51]
	s_nop 0
	v_add_f32_e32 v50, v50, v51
	s_nop 1
	v_add_f32_dpp v50, v50, v50 quad_perm:[1,0,3,2] row_mask:0xf bank_mask:0xf bound_ctrl:1
	s_nop 1
	v_add_f32_dpp v50, v50, v50 quad_perm:[2,3,0,1] row_mask:0xf bank_mask:0xf bound_ctrl:1
	s_nop 1
	v_add_f32_dpp v50, v50, v50 row_half_mirror row_mask:0xf bank_mask:0xf bound_ctrl:1
	s_nop 1
	v_add_f32_dpp v55, v50, v50 row_mirror row_mask:0xf bank_mask:0xf bound_ctrl:1
	v_pk_mul_f32 v[50:51], v[112:113], v[48:49]
	v_fmac_f32_e32 v55, 0x3fb8aa3b, v129
	v_pk_fma_f32 v[50:51], v[110:111], v[46:47], v[50:51]
	s_nop 0
	v_add_f32_e32 v50, v50, v51
	v_max_f32_e32 v51, v52, v53
	s_nop 0
	v_add_f32_dpp v50, v50, v50 quad_perm:[1,0,3,2] row_mask:0xf bank_mask:0xf bound_ctrl:1
	s_nop 1
	v_add_f32_dpp v50, v50, v50 quad_perm:[2,3,0,1] row_mask:0xf bank_mask:0xf bound_ctrl:1
	s_nop 1
	v_add_f32_dpp v50, v50, v50 row_half_mirror row_mask:0xf bank_mask:0xf bound_ctrl:1
	s_nop 1
	v_add_f32_dpp v50, v50, v50 row_mirror row_mask:0xf bank_mask:0xf bound_ctrl:1
	v_fmac_f32_e32 v50, 0x3fb8aa3b, v128
	v_max_f32_e32 v90, v55, v50
	v_max3_f32 v90, v136, v51, v90
	v_sub_f32_e32 v51, v136, v90
	v_sub_f32_e32 v50, v50, v90
	v_exp_f32_e32 v51, v51
	s_nop 0
	v_mov_b32_e32 v92, v51
	v_sub_f32_e32 v51, v52, v90
	v_exp_f32_e32 v51, v51
	s_nop 0
	v_mov_b32_e32 v94, v51
	v_sub_f32_e32 v51, v53, v90
	v_exp_f32_e32 v51, v51
	s_nop 0
	v_mov_b32_e32 v96, v51
	v_sub_f32_e32 v51, v55, v90
	v_exp_f32_e32 v51, v51
	s_nop 0
	v_mov_b32_e32 v110, v51
	v_exp_f32_e32 v50, v50
	v_pk_mul_f32 v[52:53], v[94:95], v[2:3] op_sel_hi:[0,1]
	v_pk_fma_f32 v[52:53], v[88:89], v[92:93], v[52:53] op_sel_hi:[1,0,1]
	v_mov_b32_e32 v112, v50
	v_pk_mul_f32 v[50:51], v[94:95], v[4:5] op_sel_hi:[0,1]
	v_pk_fma_f32 v[50:51], v[86:87], v[92:93], v[50:51] op_sel_hi:[1,0,1]
	v_pk_fma_f32 v[52:53], v[96:97], v[6:7], v[52:53] op_sel_hi:[0,1,1]
	v_pk_fma_f32 v[50:51], v[96:97], v[8:9], v[50:51] op_sel_hi:[0,1,1]
	v_pk_fma_f32 v[86:87], v[110:111], v[10:11], v[52:53] op_sel_hi:[0,1,1]
	v_pk_fma_f32 v[50:51], v[110:111], v[12:13], v[50:51] op_sel_hi:[0,1,1]
	v_pk_fma_f32 v[52:53], v[112:113], v[16:17], v[50:51] op_sel_hi:[0,1,1]
	v_pk_fma_f32 v[50:51], v[112:113], v[14:15], v[86:87] op_sel_hi:[0,1,1]
	v_pk_mul_f32 v[86:87], v[108:109], v[36:37]
	s_nop 0
	v_pk_fma_f32 v[86:87], v[106:107], v[34:35], v[86:87]
	s_nop 0
	v_add_f32_e32 v55, v86, v87
	v_pk_mul_f32 v[86:87], v[108:109], v[44:45]
	s_nop 0
	v_add_f32_dpp v55, v55, v55 quad_perm:[1,0,3,2] row_mask:0xf bank_mask:0xf bound_ctrl:1
	v_pk_fma_f32 v[86:87], v[106:107], v[42:43], v[86:87]
	s_nop 0
	v_add_f32_dpp v55, v55, v55 quad_perm:[2,3,0,1] row_mask:0xf bank_mask:0xf bound_ctrl:1
	s_nop 1
	v_add_f32_dpp v93, v55, v55 row_half_mirror row_mask:0xf bank_mask:0xf bound_ctrl:1
	v_add_f32_e32 v55, v86, v87
	v_pk_mul_f32 v[86:87], v[108:109], v[40:41]
	v_mov_b32_dpp v111, v93 row_mirror row_mask:0xf bank_mask:0xf bound_ctrl:1
	v_add_f32_dpp v55, v55, v55 quad_perm:[1,0,3,2] row_mask:0xf bank_mask:0xf bound_ctrl:1
	v_pk_fma_f32 v[86:87], v[106:107], v[38:39], v[86:87]
	s_nop 0
	v_add_f32_dpp v55, v55, v55 quad_perm:[2,3,0,1] row_mask:0xf bank_mask:0xf bound_ctrl:1
	s_nop 1
	v_add_f32_dpp v113, v55, v55 row_half_mirror row_mask:0xf bank_mask:0xf bound_ctrl:1
	v_add_f32_e32 v55, v86, v87
	v_pk_mul_f32 v[86:87], v[108:109], v[48:49]
	v_mov_b32_dpp v114, v113 row_mirror row_mask:0xf bank_mask:0xf bound_ctrl:1
	v_add_f32_dpp v55, v55, v55 quad_perm:[1,0,3,2] row_mask:0xf bank_mask:0xf bound_ctrl:1
	v_pk_fma_f32 v[86:87], v[106:107], v[46:47], v[86:87]
	s_nop 0
	v_add_f32_dpp v55, v55, v55 quad_perm:[2,3,0,1] row_mask:0xf bank_mask:0xf bound_ctrl:1
	s_nop 1
	v_add_f32_dpp v115, v55, v55 row_half_mirror row_mask:0xf bank_mask:0xf bound_ctrl:1
	v_add_f32_e32 v55, v86, v87
	s_nop 0
	v_mov_b32_dpp v116, v115 row_mirror row_mask:0xf bank_mask:0xf bound_ctrl:1
	v_add_f32_dpp v55, v55, v55 quad_perm:[1,0,3,2] row_mask:0xf bank_mask:0xf bound_ctrl:1
	s_nop 1
	v_add_f32_dpp v55, v55, v55 quad_perm:[2,3,0,1] row_mask:0xf bank_mask:0xf bound_ctrl:1
	s_nop 1
	v_add_f32_dpp v106, v55, v55 row_half_mirror row_mask:0xf bank_mask:0xf bound_ctrl:1
	s_nop 1
	v_mov_b32_dpp v107, v106 row_mirror row_mask:0xf bank_mask:0xf bound_ctrl:1
	v_pk_mul_f32 v[36:37], v[104:105], v[36:37]
	s_nop 0
	v_pk_fma_f32 v[34:35], v[102:103], v[34:35], v[36:37]
	s_nop 0
	v_add_f32_e32 v34, v34, v35
	s_nop 1
	v_add_f32_dpp v34, v34, v34 quad_perm:[1,0,3,2] row_mask:0xf bank_mask:0xf bound_ctrl:1
	s_nop 1
	v_add_f32_dpp v34, v34, v34 quad_perm:[2,3,0,1] row_mask:0xf bank_mask:0xf bound_ctrl:1
	s_nop 1
	v_add_f32_dpp v86, v34, v34 row_half_mirror row_mask:0xf bank_mask:0xf bound_ctrl:1
	v_pk_mul_f32 v[34:35], v[104:105], v[44:45]
	s_nop 0
	v_pk_fma_f32 v[34:35], v[102:103], v[42:43], v[34:35]
	v_mov_b32_dpp v87, v86 row_mirror row_mask:0xf bank_mask:0xf bound_ctrl:1
	v_add_f32_e32 v34, v34, v35
	s_nop 1
	v_add_f32_dpp v34, v34, v34 quad_perm:[1,0,3,2] row_mask:0xf bank_mask:0xf bound_ctrl:1
	s_nop 1
	v_add_f32_dpp v34, v34, v34 quad_perm:[2,3,0,1] row_mask:0xf bank_mask:0xf bound_ctrl:1
	s_nop 1
	v_add_f32_dpp v43, v34, v34 row_half_mirror row_mask:0xf bank_mask:0xf bound_ctrl:1
	v_pk_mul_f32 v[34:35], v[104:105], v[40:41]
	s_nop 0
	v_pk_fma_f32 v[34:35], v[102:103], v[38:39], v[34:35]
	v_mov_b32_dpp v45, v43 row_mirror row_mask:0xf bank_mask:0xf bound_ctrl:1
	v_add_f32_e32 v34, v34, v35
	s_nop 1
	v_add_f32_dpp v34, v34, v34 quad_perm:[1,0,3,2] row_mask:0xf bank_mask:0xf bound_ctrl:1
	s_nop 1
	v_add_f32_dpp v34, v34, v34 quad_perm:[2,3,0,1] row_mask:0xf bank_mask:0xf bound_ctrl:1
	s_nop 1
	v_add_f32_dpp v88, v34, v34 row_half_mirror row_mask:0xf bank_mask:0xf bound_ctrl:1
	v_pk_mul_f32 v[34:35], v[104:105], v[48:49]
	s_nop 0
	v_pk_fma_f32 v[34:35], v[102:103], v[46:47], v[34:35]
	v_mov_b32_dpp v89, v88 row_mirror row_mask:0xf bank_mask:0xf bound_ctrl:1
	v_add_f32_e32 v34, v34, v35
	s_nop 1
	v_add_f32_dpp v34, v34, v34 quad_perm:[1,0,3,2] row_mask:0xf bank_mask:0xf bound_ctrl:1
	s_nop 1
	v_add_f32_dpp v34, v34, v34 quad_perm:[2,3,0,1] row_mask:0xf bank_mask:0xf bound_ctrl:1
	s_nop 1
	v_add_f32_dpp v47, v34, v34 row_half_mirror row_mask:0xf bank_mask:0xf bound_ctrl:1
	s_nop 1
	v_mov_b32_dpp v49, v47 row_mirror row_mask:0xf bank_mask:0xf bound_ctrl:1
	s_load_dwordx2 s[0:1], s[42:43], 0x100
	v_lshl_add_u32 v40, s40, 2, v160
	v_lshlrev_b32_e32 v0, 2, v0
	v_ashrrev_i32_e32 v41, 31, v40
	v_lshlrev_b64 v[36:37], 10, v[40:41]
	s_waitcnt lgkmcnt(0)
	s_add_u32 s4, s0, 0x4f80000
	v_lshl_add_u64 v[34:35], s[0:1], 0, v[0:1]
	s_addc_u32 s5, s1, 0
	s_mov_b64 s[0:1], 0x4780000
	v_lshl_add_u64 v[34:35], v[34:35], 0, s[0:1]
	v_cmp_ne_u32_e32 vcc, 0, v159
	v_lshl_add_u64 v[36:37], v[34:35], 0, v[36:37]
	global_store_dwordx4 v[36:37], v[132:135], off
	s_and_saveexec_b64 s[0:1], vcc
	s_xor_b64 s[2:3], exec, s[0:1]
	s_cbranch_execz .LBB0_326
	global_store_dwordx4 v[36:37], v[50:53], off offset:256

.LBB0_328:
	s_or_b64 exec, exec, s[2:3]
	v_mul_f32_e32 v55, 0x3fb8aa3b, v71
	v_add_f32_e32 v0, v79, v81
	v_mul_f32_e32 v54, 0x3fb8aa3b, v69
	v_add_f32_e32 v40, v55, v0
	v_add_f32_e32 v0, v83, v85
	v_mul_f32_e32 v48, 0x3fb8aa3b, v67
	v_add_f32_e32 v42, v54, v0
	v_add_f32_e32 v0, v95, v97
	v_mul_f32_e32 v41, 0x3fb8aa3b, v146
	v_add_f32_e32 v44, v48, v0
	v_add_f32_e32 v0, v126, v127
	v_add_f32_e32 v46, v41, v0
	v_max_f32_e32 v0, v40, v42
	v_max_f32_e32 v50, v44, v46
	v_max3_f32 v74, v144, v0, v50
	v_sub_f32_e32 v0, v144, v74
	v_sub_f32_e32 v40, v40, v74
	v_sub_f32_e32 v42, v42, v74
	v_exp_f32_e32 v0, v0
	v_sub_f32_e32 v44, v44, v74
	v_exp_f32_e32 v40, v40
	v_sub_f32_e32 v46, v46, v74
	v_exp_f32_e32 v42, v42
	v_pk_mul_f32 v[52:53], v[40:41], v[22:23] op_sel_hi:[0,1]
	v_exp_f32_e32 v44, v44
	v_pk_fma_f32 v[52:53], v[124:125], v[0:1], v[52:53] op_sel_hi:[1,0,1]
	v_exp_f32_e32 v46, v46
	v_pk_fma_f32 v[52:53], v[42:43], v[18:19], v[52:53] op_sel_hi:[0,1,1]
	v_pk_fma_f32 v[52:53], v[44:45], v[26:27], v[52:53] op_sel_hi:[0,1,1]
	v_pk_mul_f32 v[50:51], v[40:41], v[24:25] op_sel_hi:[0,1]
	v_pk_fma_f32 v[50:51], v[122:123], v[0:1], v[50:51] op_sel_hi:[1,0,1]
	v_pk_fma_f32 v[68:69], v[46:47], v[30:31], v[52:53] op_sel_hi:[0,1,1]
	v_pk_fma_f32 v[50:51], v[42:43], v[20:21], v[50:51] op_sel_hi:[0,1,1]
	v_pk_fma_f32 v[50:51], v[44:45], v[28:29], v[50:51] op_sel_hi:[0,1,1]
	v_add_f32_e32 v52, v57, v77
	v_pk_fma_f32 v[66:67], v[46:47], v[32:33], v[50:51] op_sel_hi:[0,1,1]
	v_add_f32_e32 v50, v73, v75
	v_add_f32_e32 v51, v59, v61
	v_add_f32_e32 v53, v48, v52
	v_add_f32_e32 v48, v63, v65
	v_add_f32_e32 v50, v55, v50
	v_add_f32_e32 v51, v54, v51
	v_add_f32_e32 v41, v41, v48
	v_max_f32_e32 v48, v50, v51
	v_max_f32_e32 v52, v53, v41
	v_max3_f32 v55, v142, v48, v52
	v_sub_f32_e32 v48, v142, v55
	v_sub_f32_e32 v50, v50, v55
	v_sub_f32_e32 v51, v51, v55
	v_exp_f32_e32 v48, v48
	v_sub_f32_e32 v41, v41, v55
	v_exp_f32_e32 v50, v50
	v_mul_f32_e32 v64, 0x3fb8aa3b, v131
	v_exp_f32_e32 v51, v51
	v_mul_f32_e32 v62, 0x3fb8aa3b, v130
	v_mul_f32_e32 v60, 0x3fb8aa3b, v129
	v_mov_b32_e32 v52, v51
	v_sub_f32_e32 v51, v53, v55
	v_mul_f32_e32 v58, 0x3fb8aa3b, v128
	v_exp_f32_e32 v51, v51
	s_nop 0
	v_mov_b32_e32 v54, v51
	v_exp_f32_e32 v41, v41
	v_pk_mul_f32 v[22:23], v[50:51], v[22:23] op_sel_hi:[0,1]
	v_pk_fma_f32 v[22:23], v[118:119], v[48:49], v[22:23] op_sel_hi:[1,0,1]
	v_pk_mul_f32 v[24:25], v[50:51], v[24:25] op_sel_hi:[0,1]
	v_pk_fma_f32 v[18:19], v[52:53], v[18:19], v[22:23] op_sel_hi:[0,1,1]
	v_mov_b32_e32 v56, v41
	v_pk_fma_f32 v[24:25], v[120:121], v[48:49], v[24:25] op_sel_hi:[1,0,1]
	v_pk_fma_f32 v[18:19], v[54:55], v[26:27], v[18:19] op_sel_hi:[0,1,1]
	v_pk_fma_f32 v[20:21], v[52:53], v[20:21], v[24:25] op_sel_hi:[0,1,1]
	v_pk_fma_f32 v[72:73], v[56:57], v[30:31], v[18:19] op_sel_hi:[0,1,1]
	v_add_f32_e32 v18, v93, v111
	v_pk_fma_f32 v[20:21], v[54:55], v[28:29], v[20:21] op_sel_hi:[0,1,1]
	v_add_f32_e32 v19, v64, v18
	v_add_f32_e32 v18, v113, v114
	v_pk_fma_f32 v[70:71], v[56:57], v[32:33], v[20:21] op_sel_hi:[0,1,1]
	v_add_f32_e32 v21, v62, v18
	v_add_f32_e32 v18, v115, v116
	v_add_f32_e32 v23, v60, v18
	v_add_f32_e32 v18, v106, v107
	v_add_f32_e32 v25, v58, v18
	v_max_f32_e32 v18, v19, v21
	v_max_f32_e32 v20, v23, v25
	v_max3_f32 v18, v74, v18, v20
	v_sub_f32_e32 v20, v74, v18
	v_sub_f32_e32 v19, v19, v18
	v_exp_f32_e32 v20, v20
	v_exp_f32_e32 v19, v19
	s_nop 0
	v_mov_b32_e32 v22, v19
	v_sub_f32_e32 v19, v21, v18
	v_pk_mul_f32 v[30:31], v[22:23], v[4:5] op_sel_hi:[0,1]
	v_pk_mul_f32 v[32:33], v[22:23], v[2:3] op_sel_hi:[0,1]
	v_exp_f32_e32 v19, v19
	s_nop 0
	v_mov_b32_e32 v24, v19
	v_sub_f32_e32 v19, v23, v18
	v_add_f32_e32 v23, v88, v89
	v_add_f32_e32 v23, v60, v23
	v_exp_f32_e32 v19, v19
	s_nop 0
	v_mov_b32_e32 v26, v19
	v_sub_f32_e32 v19, v25, v18
	v_exp_f32_e32 v19, v19
	v_pk_fma_f32 v[32:33], v[68:69], v[20:21], v[32:33] op_sel_hi:[1,0,1]
	v_pk_fma_f32 v[30:31], v[66:67], v[20:21], v[30:31] op_sel_hi:[1,0,1]
	v_mov_b32_e32 v28, v19
	v_pk_fma_f32 v[30:31], v[24:25], v[8:9], v[30:31] op_sel_hi:[0,1,1]
	v_pk_fma_f32 v[32:33], v[24:25], v[6:7], v[32:33] op_sel_hi:[0,1,1]
	v_add_f32_e32 v19, v86, v87
	v_add_f32_e32 v21, v43, v45
	v_add_f32_e32 v25, v47, v49
	v_pk_fma_f32 v[32:33], v[26:27], v[10:11], v[32:33] op_sel_hi:[0,1,1]
	v_pk_fma_f32 v[30:31], v[26:27], v[12:13], v[30:31] op_sel_hi:[0,1,1]
	v_add_f32_e32 v19, v64, v19
	v_add_f32_e32 v21, v62, v21
	v_add_f32_e32 v25, v58, v25
	v_pk_fma_f32 v[68:69], v[28:29], v[16:17], v[30:31] op_sel_hi:[0,1,1]
	v_pk_fma_f32 v[66:67], v[28:29], v[14:15], v[32:33] op_sel_hi:[0,1,1]
	v_max_f32_e32 v27, v19, v21
	v_max_f32_e32 v29, v23, v25
	v_max3_f32 v30, v55, v27, v29
	v_sub_f32_e32 v27, v55, v30
	v_sub_f32_e32 v19, v19, v30
	v_exp_f32_e32 v27, v27
	s_nop 0
	v_mov_b32_e32 v32, v27
	v_exp_f32_e32 v19, v19
	s_nop 0
	v_mov_b32_e32 v58, v19
	v_sub_f32_e32 v19, v21, v30
	v_pk_mul_f32 v[4:5], v[58:59], v[4:5] op_sel_hi:[0,1]
	v_pk_mul_f32 v[2:3], v[58:59], v[2:3] op_sel_hi:[0,1]
	v_exp_f32_e32 v19, v19
	v_pk_fma_f32 v[2:3], v[72:73], v[32:33], v[2:3] op_sel_hi:[1,0,1]
	v_pk_fma_f32 v[4:5], v[70:71], v[32:33], v[4:5] op_sel_hi:[1,0,1]
	v_mov_b32_e32 v60, v19
	v_sub_f32_e32 v19, v23, v30
	v_pk_fma_f32 v[4:5], v[60:61], v[8:9], v[4:5] op_sel_hi:[0,1,1]
	v_pk_fma_f32 v[2:3], v[60:61], v[6:7], v[2:3] op_sel_hi:[0,1,1]
	v_exp_f32_e32 v19, v19
	v_or_b32_e32 v6, 2, v38
	v_mov_b32_e32 v7, v39
	v_mov_b32_e32 v62, v19
	v_sub_f32_e32 v19, v25, v30
	v_pk_fma_f32 v[2:3], v[62:63], v[10:11], v[2:3] op_sel_hi:[0,1,1]
	v_pk_fma_f32 v[4:5], v[62:63], v[12:13], v[4:5] op_sel_hi:[0,1,1]
	v_exp_f32_e32 v19, v19
	v_lshlrev_b64 v[8:9], 8, v[6:7]
	v_lshl_add_u64 v[8:9], v[34:35], 0, v[8:9]
	v_mov_b32_e32 v64, v19
	v_pk_fma_f32 v[4:5], v[64:65], v[16:17], v[4:5] op_sel_hi:[0,1,1]
	v_pk_fma_f32 v[2:3], v[64:65], v[14:15], v[2:3] op_sel_hi:[0,1,1]
	global_store_dwordx4 v[8:9], v[66:69], off
	s_and_saveexec_b64 s[0:1], vcc
	s_xor_b64 s[2:3], exec, s[0:1]
	s_cbranch_execnz .LBB0_330
	s_andn2_saveexec_b64 s[2:3], s[2:3]
	s_cbranch_execz .LBB0_321
	s_branch .LBB0_331
